# v41 + 7 s_nop pads in GEMM load segments so every 32-MFMA run starts 8-byte aligned (code placement)
# baseline (speedup 1.0000x reference)
;     __device__ __forceinline__ void prefetch(const Unit& u, int ui) const { if (rs) rs_prefetch(rs, u.pm, ui); }
;     __device__ __forceinline__ void prefetch(const Unit& u, int ui) const { rs_prefetch(rs, u.pm, ui); }
; #define PG8_STAGE(bufoff, gbase, voff) do { _Pragma("unroll") for (int _i = 0; _i < 2; ++_i) \
;         __builtin_amdgcn_global_load_lds((const unsigned*)((const char*)(gbase) + (voff)[_i]), (LAS unsigned*)(lds + (bufoff) + ldsw + _i * 8192), 16, 0, 0); } while (0)
; #define PG8_LDA(dst, b, h) do { _Pragma("unroll") for (int m = 0; m < 4; ++m) _Pragma("unroll") for (int k = 0; k < 2; ++k) dst[m][k] = *(const LAS bf16x8*)(lds + PG8_SA(b, h) + aoff + m * 2048 + k * 1024); } while (0)
; template <class Epi, class Sched>
; __device__ __forceinline__ void gemm_phase(LAS unsigned char* lds, const Gemm g, const Sched& S, const Epi& E) {
;     ...
;     for (;;) {
;         E.prefetch(cur, ui);
;         const bool has_next = S.next(ui + 1, nxt);
;         const char* nA = has_next ? (const char*)g.A + (size_t)nxt.pm * tstepA : cA; const char* nB = has_next ? (const char*)g.Bt + (size_t)nxt.pn * tstepB : cB;
;         for (int t = 0; t < nt; t += 2) {
;             const bool last = (t == nt - 2);
;             const char* a1 = cA + (size_t)(t + 1) * kstep;
;             const char* a2 = last ? nA : cA + (size_t)(t + 2) * kstep; const char* b2 = last ? nB : cB + (size_t)(t + 2) * kstep;
;             const char* a3 = a2 + kstep; const char* b3 = b2 + kstep;
;             if (last && has_next) S.a_ready(nxt);
;             PG8_LDB(B0, 0, 0); PG8_SCHED; PG8_LDA(At, 0, 0); PG8_STAGE(PG8_SA(1, 1), a1 + hstepA, voffA);
;             PG8_WAIT_L(8); PG8_BAR; PG8_WAIT_L(0); PG8_MMA(0, 0, At, B0); PG8_BAR; PG8_SCHED;
;             PG8_LDB(B1, 0, 1); PG8_STAGE(PG8_SB(0, 0), b2, voffB);
;             PG8_BAR; PG8_WAIT_L(0); PG8_MMA(0, 1, At, B1); PG8_BAR;
;             PG8_LDA(At, 0, 1); PG8_STAGE(PG8_SA(0, 0), a2, voffA);
;             PG8_BAR; PG8_WAIT_L(0); PG8_MMA(1, 0, At, B0); PG8_BAR; PG8_SCHED;
;             PG8_STAGE(PG8_SB(0, 1), b2 + hstepB, voffB);
;             PG8_WAIT_V(6); PG8_BAR; PG8_MMA(1, 1, At, B1); PG8_BAR;
;             PG8_LDB(B0, 1, 0); PG8_SCHED; PG8_LDA(At, 1, 0); PG8_STAGE(PG8_SA(0, 1), a2 + hstepA, voffA);
;             PG8_WAIT_L(8); PG8_BAR; PG8_WAIT_L(0); PG8_MMA(0, 0, At, B0); PG8_BAR; PG8_SCHED;
.LBB0_490:
	s_ashr_i32 s53, s52, 31
	s_lshl_b64 s[18:19], s[52:53], 20
	s_add_u32 s54, s25, s18
	v_cmp_lt_i64_e64 s[14:15], s[14:15], 16
	s_addc_u32 s55, s28, s19
	s_and_b64 s[18:19], s[14:15], exec
	s_cselect_b32 s18, s55, s5
	s_cselect_b32 s19, s54, s4
	s_ashr_i32 s51, s50, 31
	s_lshl_b64 s[56:57], s[50:51], 21
	s_add_u32 s56, s44, s56
	s_addc_u32 s57, s45, s57
	s_and_b64 s[14:15], s[14:15], exec
	s_cselect_b32 s51, s57, s7
	s_cselect_b32 s53, s56, s6
	s_add_u32 s4, s4, 0x80080
	s_addc_u32 s5, s5, 0
	s_add_u32 s65, s6, 0x100
	s_addc_u32 s66, s7, 0
	s_mov_b32 s67, -2
	s_waitcnt lgkmcnt(0)
	s_add_u32 s6, s4, 0xfff80080
	s_addc_u32 s7, s5, -1
	s_add_i32 s68, 0, 0x10000
	v_add_u32_e32 v154, s68, v1
	ds_read_b128 v[142:145], v154
	ds_read_b128 v[146:149], v154 offset:1024
	ds_read_b128 v[150:153], v154 offset:2048
	ds_read_b128 v[158:161], v154 offset:3072
	s_cmp_eq_u32 s67, 60
	s_cselect_b32 s15, s18, s7
	s_cselect_b32 s14, s19, s6
	s_cselect_b32 s7, s51, s66
	s_cselect_b32 s6, s53, s65
	ds_read_b128 v[162:165], v156
	ds_read_b128 v[166:169], v156 offset:1024
	ds_read_b128 v[170:173], v156 offset:2048
	ds_read_b128 v[174:177], v156 offset:3072
	ds_read_b128 v[178:181], v156 offset:4096
	ds_read_b128 v[182:185], v156 offset:5120
	ds_read_b128 v[186:189], v156 offset:6144
	ds_read_b128 v[190:193], v156 offset:7168
	s_add_i32 s70, 0, 0x14000
	v_add_u32_e32 v154, s70, v1
	ds_read_b128 v[194:197], v154
	ds_read_b128 v[198:201], v154 offset:1024
	ds_read_b128 v[202:205], v154 offset:2048
	ds_read_b128 v[206:209], v154 offset:3072
	s_add_i32 m0, s30, 0xc000
	s_nop 0
	global_load_lds_dwordx4 v138, s[4:5]
	s_add_i32 m0, s30, 0xe000
	s_nop 0
	global_load_lds_dwordx4 v140, s[4:5]
	s_nop 0
	s_waitcnt lgkmcnt(0)
	s_barrier
	v_mfma_f32_16x16x32_bf16 v[128:131], v[142:145], v[162:165], 0
	v_mfma_f32_16x16x32_bf16 v[124:127], v[150:153], v[162:165], 0
	v_mfma_f32_16x16x32_bf16 v[120:123], v[142:145], v[170:173], 0
	v_mfma_f32_16x16x32_bf16 v[116:119], v[150:153], v[170:173], 0
	v_mfma_f32_16x16x32_bf16 v[112:115], v[142:145], v[178:181], 0
	v_mfma_f32_16x16x32_bf16 v[108:111], v[150:153], v[178:181], 0
	v_mfma_f32_16x16x32_bf16 v[104:107], v[142:145], v[186:189], 0
	v_mfma_f32_16x16x32_bf16 v[100:103], v[150:153], v[186:189], 0
	v_mfma_f32_16x16x32_bf16 v[128:131], v[146:149], v[166:169], v[128:131]
	v_mfma_f32_16x16x32_bf16 v[124:127], v[158:161], v[166:169], v[124:127]
	v_mfma_f32_16x16x32_bf16 v[120:123], v[146:149], v[174:177], v[120:123]
	v_mfma_f32_16x16x32_bf16 v[116:119], v[158:161], v[174:177], v[116:119]
	v_mfma_f32_16x16x32_bf16 v[112:115], v[146:149], v[182:185], v[112:115]
	v_mfma_f32_16x16x32_bf16 v[108:111], v[158:161], v[182:185], v[108:111]
	v_mfma_f32_16x16x32_bf16 v[104:107], v[146:149], v[190:193], v[104:107]
	v_mfma_f32_16x16x32_bf16 v[100:103], v[158:161], v[190:193], v[100:103]
	v_mfma_f32_16x16x32_bf16 v[64:67], v[194:197], v[162:165], 0
	v_mfma_f32_16x16x32_bf16 v[60:63], v[202:205], v[162:165], 0
	v_mfma_f32_16x16x32_bf16 v[56:59], v[194:197], v[170:173], 0
	v_mfma_f32_16x16x32_bf16 v[52:55], v[202:205], v[170:173], 0
	v_mfma_f32_16x16x32_bf16 v[48:51], v[194:197], v[178:181], 0
	v_mfma_f32_16x16x32_bf16 v[44:47], v[202:205], v[178:181], 0
	v_mfma_f32_16x16x32_bf16 v[40:43], v[194:197], v[186:189], 0
	v_mfma_f32_16x16x32_bf16 v[36:39], v[202:205], v[186:189], 0
	v_mfma_f32_16x16x32_bf16 v[64:67], v[198:201], v[166:169], v[64:67]
	v_mfma_f32_16x16x32_bf16 v[60:63], v[206:209], v[166:169], v[60:63]
	v_mfma_f32_16x16x32_bf16 v[56:59], v[198:201], v[174:177], v[56:59]
	v_mfma_f32_16x16x32_bf16 v[52:55], v[206:209], v[174:177], v[52:55]
	v_mfma_f32_16x16x32_bf16 v[48:51], v[198:201], v[182:185], v[48:51]
	v_mfma_f32_16x16x32_bf16 v[44:47], v[206:209], v[182:185], v[44:47]
	v_mfma_f32_16x16x32_bf16 v[40:43], v[198:201], v[190:193], v[40:43]
	v_mfma_f32_16x16x32_bf16 v[36:39], v[206:209], v[190:193], v[36:39]
	s_barrier
	ds_read_b128 v[162:165], v156 offset:16384
	ds_read_b128 v[166:169], v156 offset:17408
	ds_read_b128 v[170:173], v156 offset:18432
	ds_read_b128 v[174:177], v156 offset:19456
	ds_read_b128 v[178:181], v156 offset:20480
	ds_read_b128 v[182:185], v156 offset:21504
	ds_read_b128 v[186:189], v156 offset:22528
	ds_read_b128 v[190:193], v156 offset:23552
	s_add_i32 s68, s68, s29
	v_lshl_add_u64 v[154:155], s[6:7], 0, v[2:3]
	s_mov_b32 m0, s68
	v_lshl_add_u64 v[210:211], s[6:7], 0, v[136:137]
	global_load_lds_dwordx4 v[154:155], off
	s_add_i32 m0, s68, 0x2000
	s_nop 0
	global_load_lds_dwordx4 v[210:211], off
	s_mov_b32 m0, s30
	v_lshl_add_u64 v[212:213], s[14:15], 0, v[132:133]
	global_load_lds_dwordx4 v[212:213], off
	v_lshl_add_u64 v[216:217], s[14:15], 0, v[134:135]
	s_mov_b32 m0, s31
	s_nop 0
	global_load_lds_dwordx4 v[216:217], off
	s_add_u32 s68, s6, 0x100000
	s_addc_u32 s69, s7, 0
	s_add_i32 s70, s70, s29
	s_mov_b32 m0, s70
	s_nop 0
	global_load_lds_dwordx4 v2, s[68:69]
	s_add_i32 m0, s70, 0x2000
	s_nop 0
	global_load_lds_dwordx4 v136, s[68:69]
	s_nop 0
	s_waitcnt lgkmcnt(0)
	s_waitcnt vmcnt(6)
	s_barrier
; #define PG8_STAGE(bufoff, gbase, voff) do { _Pragma("unroll") for (int _i = 0; _i < 2; ++_i) \
;         __builtin_amdgcn_global_load_lds((const unsigned*)((const char*)(gbase) + (voff)[_i]), (LAS unsigned*)(lds + (bufoff) + ldsw + _i * 8192), 16, 0, 0); } while (0)
; #define PG8_LDA(dst, b, h) do { _Pragma("unroll") for (int m = 0; m < 4; ++m) _Pragma("unroll") for (int k = 0; k < 2; ++k) dst[m][k] = *(const LAS bf16x8*)(lds + PG8_SA(b, h) + aoff + m * 2048 + k * 1024); } while (0)
; #define PG8_LDB(dst, b, h) do { _Pragma("unroll") for (int n = 0; n < 2; ++n) _Pragma("unroll") for (int k = 0; k < 2; ++k) dst[n][k] = *(const LAS bf16x8*)(lds + PG8_SB(b, h) + boff + n * 2048 + k * 1024); } while (0)
; #define PG8_MMA(ai, bj, At, Bt) do { __builtin_amdgcn_s_setprio(1); _Pragma("unroll") for (int m = 0; m < 4; ++m) _Pragma("unroll") for (int n = 0; n < 2; ++n) _Pragma("unroll") for (int k = 0; k < 2; ++k) \
;         acc[ai][bj][m][n] = __builtin_amdgcn_mfma_f32_16x16x32_bf16(Bt[n][k], At[m][k], acc[ai][bj][m][n], 0, 0, 0); __builtin_amdgcn_s_setprio(0); } while (0)
; #define PG8_WAIT_V(n) asm volatile("s_waitcnt vmcnt(" #n ")" ::: "memory")
; #define PG8_WAIT_L(n) asm volatile("s_waitcnt lgkmcnt(" #n ")" ::: "memory")
; #define PG8_BAR __builtin_amdgcn_s_barrier()
; #define PG8_SCHED __builtin_amdgcn_sched_barrier(0)
; template <class Epi, class Sched>
; __device__ __forceinline__ void gemm_phase(LAS unsigned char* lds, const Gemm g, const Sched& S, const Epi& E) {
;     ...
;             PG8_BAR; PG8_WAIT_L(0); PG8_MMA(1, 0, At, B0); PG8_BAR; PG8_SCHED;
;             PG8_STAGE(PG8_SB(0, 1), b2 + hstepB, voffB);
;             PG8_WAIT_V(6); PG8_BAR; PG8_MMA(1, 1, At, B1); PG8_BAR;
;             PG8_LDB(B0, 1, 0); PG8_SCHED; PG8_LDA(At, 1, 0); PG8_STAGE(PG8_SA(0, 1), a2 + hstepA, voffA);
;             PG8_WAIT_L(8); PG8_BAR; PG8_WAIT_L(0); PG8_MMA(0, 0, At, B0); PG8_BAR; PG8_SCHED;
;             PG8_LDB(B1, 1, 1); PG8_STAGE(PG8_SB(1, 0), b3, voffB);
;             PG8_BAR; PG8_WAIT_L(0); PG8_MMA(0, 1, At, B1); PG8_BAR;
;             PG8_LDA(At, 1, 1); PG8_STAGE(PG8_SA(1, 0), a3, voffA);
;             PG8_BAR; PG8_WAIT_L(0); PG8_MMA(1, 0, At, B0); PG8_BAR; PG8_SCHED;
	v_mfma_f32_16x16x32_bf16 v[96:99], v[142:145], v[162:165], 0
	v_mfma_f32_16x16x32_bf16 v[92:95], v[150:153], v[162:165], 0
	v_mfma_f32_16x16x32_bf16 v[88:91], v[142:145], v[170:173], 0
	v_mfma_f32_16x16x32_bf16 v[84:87], v[150:153], v[170:173], 0
	v_mfma_f32_16x16x32_bf16 v[80:83], v[142:145], v[178:181], 0
	v_mfma_f32_16x16x32_bf16 v[76:79], v[150:153], v[178:181], 0
	v_mfma_f32_16x16x32_bf16 v[72:75], v[142:145], v[186:189], 0
	v_mfma_f32_16x16x32_bf16 v[68:71], v[150:153], v[186:189], 0
	v_mfma_f32_16x16x32_bf16 v[96:99], v[146:149], v[166:169], v[96:99]
	v_mfma_f32_16x16x32_bf16 v[92:95], v[158:161], v[166:169], v[92:95]
	v_mfma_f32_16x16x32_bf16 v[88:91], v[146:149], v[174:177], v[88:91]
	v_mfma_f32_16x16x32_bf16 v[84:87], v[158:161], v[174:177], v[84:87]
	v_mfma_f32_16x16x32_bf16 v[80:83], v[146:149], v[182:185], v[80:83]
	v_mfma_f32_16x16x32_bf16 v[76:79], v[158:161], v[182:185], v[76:79]
	v_mfma_f32_16x16x32_bf16 v[72:75], v[146:149], v[190:193], v[72:75]
	v_mfma_f32_16x16x32_bf16 v[68:71], v[158:161], v[190:193], v[68:71]
	v_mfma_f32_16x16x32_bf16 v[32:35], v[194:197], v[162:165], 0
	v_mfma_f32_16x16x32_bf16 v[28:31], v[202:205], v[162:165], 0
	v_mfma_f32_16x16x32_bf16 v[24:27], v[194:197], v[170:173], 0
	v_mfma_f32_16x16x32_bf16 v[20:23], v[202:205], v[170:173], 0
	v_mfma_f32_16x16x32_bf16 v[16:19], v[194:197], v[178:181], 0
	v_mfma_f32_16x16x32_bf16 v[12:15], v[202:205], v[178:181], 0
	v_mfma_f32_16x16x32_bf16 v[8:11], v[194:197], v[186:189], 0
	v_mfma_f32_16x16x32_bf16 v[4:7], v[202:205], v[186:189], 0
	v_mfma_f32_16x16x32_bf16 v[32:35], v[198:201], v[166:169], v[32:35]
	v_mfma_f32_16x16x32_bf16 v[28:31], v[206:209], v[166:169], v[28:31]
	v_mfma_f32_16x16x32_bf16 v[24:27], v[198:201], v[174:177], v[24:27]
	v_mfma_f32_16x16x32_bf16 v[20:23], v[206:209], v[174:177], v[20:23]
	v_mfma_f32_16x16x32_bf16 v[16:19], v[198:201], v[182:185], v[16:19]
	v_mfma_f32_16x16x32_bf16 v[12:15], v[206:209], v[182:185], v[12:15]
	v_mfma_f32_16x16x32_bf16 v[8:11], v[198:201], v[190:193], v[8:11]
	v_mfma_f32_16x16x32_bf16 v[4:7], v[206:209], v[190:193], v[4:7]
	s_barrier
	s_add_i32 s68, 0, 0x18000
	v_add_u32_e32 v157, s68, v1
	ds_read_b128 v[142:145], v157
	ds_read_b128 v[146:149], v157 offset:1024
	ds_read_b128 v[150:153], v157 offset:2048
	ds_read_b128 v[158:161], v157 offset:3072
	s_add_u32 s14, s14, 0x80000
	s_addc_u32 s15, s15, 0
	ds_read_b128 v[162:165], v156 offset:32768
	ds_read_b128 v[166:169], v156 offset:33792
	ds_read_b128 v[170:173], v156 offset:34816
	ds_read_b128 v[174:177], v156 offset:35840
	ds_read_b128 v[178:181], v156 offset:36864
	ds_read_b128 v[182:185], v156 offset:37888
	ds_read_b128 v[186:189], v156 offset:38912
	ds_read_b128 v[190:193], v156 offset:39936
	s_mov_b32 m0, s38
	s_nop 0
	global_load_lds_dwordx4 v132, s[14:15]
	s_mov_b32 m0, s39
	s_nop 0
	global_load_lds_dwordx4 v134, s[14:15]
	s_add_i32 s14, 0, 0x1c000
	v_add_u32_e32 v157, s14, v1
	ds_read_b128 v[194:197], v157
	ds_read_b128 v[198:201], v157 offset:1024
	ds_read_b128 v[202:205], v157 offset:2048
	ds_read_b128 v[206:209], v157 offset:3072
	s_waitcnt lgkmcnt(0)
	s_barrier
	v_mfma_f32_16x16x32_bf16 v[128:131], v[142:145], v[162:165], v[128:131]
	v_mfma_f32_16x16x32_bf16 v[124:127], v[150:153], v[162:165], v[124:127]
	v_mfma_f32_16x16x32_bf16 v[120:123], v[142:145], v[170:173], v[120:123]
	v_mfma_f32_16x16x32_bf16 v[116:119], v[150:153], v[170:173], v[116:119]
	v_mfma_f32_16x16x32_bf16 v[112:115], v[142:145], v[178:181], v[112:115]
	v_mfma_f32_16x16x32_bf16 v[108:111], v[150:153], v[178:181], v[108:111]
	v_mfma_f32_16x16x32_bf16 v[104:107], v[142:145], v[186:189], v[104:107]
	v_mfma_f32_16x16x32_bf16 v[100:103], v[150:153], v[186:189], v[100:103]
	v_mfma_f32_16x16x32_bf16 v[128:131], v[146:149], v[166:169], v[128:131]
	v_mfma_f32_16x16x32_bf16 v[124:127], v[158:161], v[166:169], v[124:127]
	v_mfma_f32_16x16x32_bf16 v[120:123], v[146:149], v[174:177], v[120:123]
	v_mfma_f32_16x16x32_bf16 v[116:119], v[158:161], v[174:177], v[116:119]
	v_mfma_f32_16x16x32_bf16 v[112:115], v[146:149], v[182:185], v[112:115]
	v_mfma_f32_16x16x32_bf16 v[108:111], v[158:161], v[182:185], v[108:111]
	v_mfma_f32_16x16x32_bf16 v[104:107], v[146:149], v[190:193], v[104:107]
	v_mfma_f32_16x16x32_bf16 v[100:103], v[158:161], v[190:193], v[100:103]
	v_mfma_f32_16x16x32_bf16 v[64:67], v[194:197], v[162:165], v[64:67]
	v_mfma_f32_16x16x32_bf16 v[60:63], v[202:205], v[162:165], v[60:63]
	v_mfma_f32_16x16x32_bf16 v[56:59], v[194:197], v[170:173], v[56:59]
	v_mfma_f32_16x16x32_bf16 v[52:55], v[202:205], v[170:173], v[52:55]
	v_mfma_f32_16x16x32_bf16 v[48:51], v[194:197], v[178:181], v[48:51]
	v_mfma_f32_16x16x32_bf16 v[44:47], v[202:205], v[178:181], v[44:47]
	v_mfma_f32_16x16x32_bf16 v[40:43], v[194:197], v[186:189], v[40:43]
	v_mfma_f32_16x16x32_bf16 v[36:39], v[202:205], v[186:189], v[36:39]
	v_mfma_f32_16x16x32_bf16 v[64:67], v[198:201], v[166:169], v[64:67]
	v_mfma_f32_16x16x32_bf16 v[60:63], v[206:209], v[166:169], v[60:63]
	v_mfma_f32_16x16x32_bf16 v[56:59], v[198:201], v[174:177], v[56:59]
	v_mfma_f32_16x16x32_bf16 v[52:55], v[206:209], v[174:177], v[52:55]
	v_mfma_f32_16x16x32_bf16 v[48:51], v[198:201], v[182:185], v[48:51]
	v_mfma_f32_16x16x32_bf16 v[44:47], v[206:209], v[182:185], v[44:47]
	v_mfma_f32_16x16x32_bf16 v[40:43], v[198:201], v[190:193], v[40:43]
	v_mfma_f32_16x16x32_bf16 v[36:39], v[206:209], v[190:193], v[36:39]
	s_barrier
; #define PG8_STAGE(bufoff, gbase, voff) do { _Pragma("unroll") for (int _i = 0; _i < 2; ++_i) \
;         __builtin_amdgcn_global_load_lds((const unsigned*)((const char*)(gbase) + (voff)[_i]), (LAS unsigned*)(lds + (bufoff) + ldsw + _i * 8192), 16, 0, 0); } while (0)
; #define PG8_LDA(dst, b, h) do { _Pragma("unroll") for (int m = 0; m < 4; ++m) _Pragma("unroll") for (int k = 0; k < 2; ++k) dst[m][k] = *(const LAS bf16x8*)(lds + PG8_SA(b, h) + aoff + m * 2048 + k * 1024); } while (0)
; #define PG8_LDB(dst, b, h) do { _Pragma("unroll") for (int n = 0; n < 2; ++n) _Pragma("unroll") for (int k = 0; k < 2; ++k) dst[n][k] = *(const LAS bf16x8*)(lds + PG8_SB(b, h) + boff + n * 2048 + k * 1024); } while (0)
; #define PG8_MMA(ai, bj, At, Bt) do { __builtin_amdgcn_s_setprio(1); _Pragma("unroll") for (int m = 0; m < 4; ++m) _Pragma("unroll") for (int n = 0; n < 2; ++n) _Pragma("unroll") for (int k = 0; k < 2; ++k) \
;         acc[ai][bj][m][n] = __builtin_amdgcn_mfma_f32_16x16x32_bf16(Bt[n][k], At[m][k], acc[ai][bj][m][n], 0, 0, 0); __builtin_amdgcn_s_setprio(0); } while (0)
; #define PG8_WAIT_V(n) asm volatile("s_waitcnt vmcnt(" #n ")" ::: "memory")
; #define PG8_WAIT_L(n) asm volatile("s_waitcnt lgkmcnt(" #n ")" ::: "memory")
; #define PG8_BAR __builtin_amdgcn_s_barrier()
; #define PG8_SCHED __builtin_amdgcn_sched_barrier(0)
; template <class Epi, class Sched>
; __device__ __forceinline__ void gemm_phase(LAS unsigned char* lds, const Gemm g, const Sched& S, const Epi& E) {
;     ...
;         for (int t = 0; t < nt; t += 2) {
;             const bool last = (t == nt - 2);
;             const char* a1 = cA + (size_t)(t + 1) * kstep;
;             const char* a2 = last ? nA : cA + (size_t)(t + 2) * kstep; const char* b2 = last ? nB : cB + (size_t)(t + 2) * kstep;
;             const char* a3 = a2 + kstep; const char* b3 = b2 + kstep;
;             if (last && has_next) S.a_ready(nxt);
;             PG8_LDB(B0, 0, 0); PG8_SCHED; PG8_LDA(At, 0, 0); PG8_STAGE(PG8_SA(1, 1), a1 + hstepA, voffA);
;             PG8_WAIT_L(8); PG8_BAR; PG8_WAIT_L(0); PG8_MMA(0, 0, At, B0); PG8_BAR; PG8_SCHED;
;     ...
;             PG8_LDA(At, 1, 1); PG8_STAGE(PG8_SA(1, 0), a3, voffA);
;             PG8_BAR; PG8_WAIT_L(0); PG8_MMA(1, 0, At, B0); PG8_BAR; PG8_SCHED;
;             PG8_STAGE(PG8_SB(1, 1), b3 + hstepB, voffB);
;             PG8_WAIT_V(6); PG8_BAR; PG8_MMA(1, 1, At, B1); PG8_BAR;
	ds_read_b128 v[162:165], v156 offset:49152
	ds_read_b128 v[166:169], v156 offset:50176
	ds_read_b128 v[170:173], v156 offset:51200
	ds_read_b128 v[174:177], v156 offset:52224
	ds_read_b128 v[178:181], v156 offset:53248
	ds_read_b128 v[182:185], v156 offset:54272
	ds_read_b128 v[186:189], v156 offset:55296
	ds_read_b128 v[190:193], v156 offset:56320
	s_add_i32 s15, s68, s29
	v_lshl_add_u64 v[154:155], v[154:155], 0, s[8:9]
	s_mov_b32 m0, s15
	s_nop 0
	global_load_lds_dwordx4 v[154:155], off
	v_lshl_add_u64 v[154:155], v[210:211], 0, s[8:9]
	s_add_i32 m0, s15, 0x2000
	s_nop 0
	global_load_lds_dwordx4 v[154:155], off
	s_mov_b32 m0, s62
	v_lshl_add_u64 v[154:155], v[212:213], 0, s[8:9]
	global_load_lds_dwordx4 v[154:155], off
	v_lshl_add_u64 v[154:155], v[216:217], 0, s[8:9]
	s_mov_b32 m0, s63
	s_nop 0
	global_load_lds_dwordx4 v[154:155], off
	s_add_u32 s6, s6, 0x100080
	s_addc_u32 s7, s7, 0
	s_add_i32 s14, s14, s29
	s_mov_b32 m0, s14
	s_nop 0
	global_load_lds_dwordx4 v2, s[6:7]
	s_add_i32 m0, s14, 0x2000
	s_nop 0
	global_load_lds_dwordx4 v136, s[6:7]
	s_add_i32 s67, s67, 2
	s_add_u32 s4, s4, 0x100
	s_addc_u32 s5, s5, 0
	s_add_u32 s65, s65, 0x100
	s_addc_u32 s66, s66, 0
	s_cmp_gt_u32 s67, 61
	s_waitcnt lgkmcnt(0)
	s_waitcnt vmcnt(6)
	s_barrier
	v_mfma_f32_16x16x32_bf16 v[96:99], v[142:145], v[162:165], v[96:99]
	v_mfma_f32_16x16x32_bf16 v[92:95], v[150:153], v[162:165], v[92:95]
	v_mfma_f32_16x16x32_bf16 v[88:91], v[142:145], v[170:173], v[88:91]
	v_mfma_f32_16x16x32_bf16 v[84:87], v[150:153], v[170:173], v[84:87]
	v_mfma_f32_16x16x32_bf16 v[80:83], v[142:145], v[178:181], v[80:83]
	v_mfma_f32_16x16x32_bf16 v[76:79], v[150:153], v[178:181], v[76:79]
	v_mfma_f32_16x16x32_bf16 v[72:75], v[142:145], v[186:189], v[72:75]
	v_mfma_f32_16x16x32_bf16 v[68:71], v[150:153], v[186:189], v[68:71]
	v_mfma_f32_16x16x32_bf16 v[96:99], v[146:149], v[166:169], v[96:99]
	v_mfma_f32_16x16x32_bf16 v[92:95], v[158:161], v[166:169], v[92:95]
	v_mfma_f32_16x16x32_bf16 v[88:91], v[146:149], v[174:177], v[88:91]
	v_mfma_f32_16x16x32_bf16 v[84:87], v[158:161], v[174:177], v[84:87]
	v_mfma_f32_16x16x32_bf16 v[80:83], v[146:149], v[182:185], v[80:83]
	v_mfma_f32_16x16x32_bf16 v[76:79], v[158:161], v[182:185], v[76:79]
	v_mfma_f32_16x16x32_bf16 v[72:75], v[146:149], v[190:193], v[72:75]
	v_mfma_f32_16x16x32_bf16 v[68:71], v[158:161], v[190:193], v[68:71]
	v_mfma_f32_16x16x32_bf16 v[32:35], v[194:197], v[162:165], v[32:35]
	v_mfma_f32_16x16x32_bf16 v[28:31], v[202:205], v[162:165], v[28:31]
	v_mfma_f32_16x16x32_bf16 v[24:27], v[194:197], v[170:173], v[24:27]
	v_mfma_f32_16x16x32_bf16 v[20:23], v[202:205], v[170:173], v[20:23]
	v_mfma_f32_16x16x32_bf16 v[16:19], v[194:197], v[178:181], v[16:19]
	v_mfma_f32_16x16x32_bf16 v[12:15], v[202:205], v[178:181], v[12:15]
	v_mfma_f32_16x16x32_bf16 v[8:11], v[194:197], v[186:189], v[8:11]
	v_mfma_f32_16x16x32_bf16 v[4:7], v[202:205], v[186:189], v[4:7]
	v_mfma_f32_16x16x32_bf16 v[32:35], v[198:201], v[166:169], v[32:35]
	v_mfma_f32_16x16x32_bf16 v[28:31], v[206:209], v[166:169], v[28:31]
	v_mfma_f32_16x16x32_bf16 v[24:27], v[198:201], v[174:177], v[24:27]
	v_mfma_f32_16x16x32_bf16 v[20:23], v[206:209], v[174:177], v[20:23]
	v_mfma_f32_16x16x32_bf16 v[16:19], v[198:201], v[182:185], v[16:19]
	v_mfma_f32_16x16x32_bf16 v[12:15], v[206:209], v[182:185], v[12:15]
	v_mfma_f32_16x16x32_bf16 v[8:11], v[198:201], v[190:193], v[8:11]
	v_mfma_f32_16x16x32_bf16 v[4:7], v[206:209], v[190:193], v[4:7]
	s_barrier
	s_setprio 0
.LBB0_491:
	s_add_u32 s6, s4, 0xfff80080
	s_addc_u32 s7, s5, -1
	s_add_i32 s68, 0, 0x10000
	v_add_u32_e32 v154, s68, v1
	ds_read_b128 v[142:145], v154
	ds_read_b128 v[146:149], v154 offset:1024
	ds_read_b128 v[150:153], v154 offset:2048
	ds_read_b128 v[158:161], v154 offset:3072
	s_cmp_eq_u32 s67, 60
	s_cselect_b32 s15, s18, s7
	s_cselect_b32 s14, s19, s6
	s_cselect_b32 s7, s51, s66
	s_cselect_b32 s6, s53, s65
	ds_read_b128 v[162:165], v156
	ds_read_b128 v[166:169], v156 offset:1024
	ds_read_b128 v[170:173], v156 offset:2048
	ds_read_b128 v[174:177], v156 offset:3072
	ds_read_b128 v[178:181], v156 offset:4096
	ds_read_b128 v[182:185], v156 offset:5120
	ds_read_b128 v[186:189], v156 offset:6144
	ds_read_b128 v[190:193], v156 offset:7168
	s_add_i32 s70, 0, 0x14000
	v_add_u32_e32 v154, s70, v1
	ds_read_b128 v[194:197], v154
	ds_read_b128 v[198:201], v154 offset:1024
	ds_read_b128 v[202:205], v154 offset:2048
	ds_read_b128 v[206:209], v154 offset:3072
	s_add_i32 m0, s30, 0xc000
	s_nop 0
	global_load_lds_dwordx4 v138, s[4:5]
	s_add_i32 m0, s30, 0xe000
	s_nop 0
	global_load_lds_dwordx4 v140, s[4:5]
	s_waitcnt lgkmcnt(0)
	s_barrier
; #define PG8_STAGE(bufoff, gbase, voff) do { _Pragma("unroll") for (int _i = 0; _i < 2; ++_i) \
;         __builtin_amdgcn_global_load_lds((const unsigned*)((const char*)(gbase) + (voff)[_i]), (LAS unsigned*)(lds + (bufoff) + ldsw + _i * 8192), 16, 0, 0); } while (0)
; #define PG8_LDA(dst, b, h) do { _Pragma("unroll") for (int m = 0; m < 4; ++m) _Pragma("unroll") for (int k = 0; k < 2; ++k) dst[m][k] = *(const LAS bf16x8*)(lds + PG8_SA(b, h) + aoff + m * 2048 + k * 1024); } while (0)
; #define PG8_LDB(dst, b, h) do { _Pragma("unroll") for (int n = 0; n < 2; ++n) _Pragma("unroll") for (int k = 0; k < 2; ++k) dst[n][k] = *(const LAS bf16x8*)(lds + PG8_SB(b, h) + boff + n * 2048 + k * 1024); } while (0)
; #define PG8_MMA(ai, bj, At, Bt) do { __builtin_amdgcn_s_setprio(1); _Pragma("unroll") for (int m = 0; m < 4; ++m) _Pragma("unroll") for (int n = 0; n < 2; ++n) _Pragma("unroll") for (int k = 0; k < 2; ++k) \
;         acc[ai][bj][m][n] = __builtin_amdgcn_mfma_f32_16x16x32_bf16(Bt[n][k], At[m][k], acc[ai][bj][m][n], 0, 0, 0); __builtin_amdgcn_s_setprio(0); } while (0)
; #define PG8_WAIT_V(n) asm volatile("s_waitcnt vmcnt(" #n ")" ::: "memory")
; #define PG8_WAIT_L(n) asm volatile("s_waitcnt lgkmcnt(" #n ")" ::: "memory")
; #define PG8_BAR __builtin_amdgcn_s_barrier()
; #define PG8_SCHED __builtin_amdgcn_sched_barrier(0)
; template <class Epi, class Sched>
; __device__ __forceinline__ void gemm_phase(LAS unsigned char* lds, const Gemm g, const Sched& S, const Epi& E) {
;     ...
;             PG8_WAIT_L(8); PG8_BAR; PG8_WAIT_L(0); PG8_MMA(0, 0, At, B0); PG8_BAR; PG8_SCHED;
;             PG8_LDB(B1, 0, 1); PG8_STAGE(PG8_SB(0, 0), b2, voffB);
;             PG8_BAR; PG8_WAIT_L(0); PG8_MMA(0, 1, At, B1); PG8_BAR;
;             PG8_LDA(At, 0, 1); PG8_STAGE(PG8_SA(0, 0), a2, voffA);
;             PG8_BAR; PG8_WAIT_L(0); PG8_MMA(1, 0, At, B0); PG8_BAR; PG8_SCHED;
;             PG8_STAGE(PG8_SB(0, 1), b2 + hstepB, voffB);
;             PG8_WAIT_V(6); PG8_BAR; PG8_MMA(1, 1, At, B1); PG8_BAR;
	v_mfma_f32_16x16x32_bf16 v[128:131], v[142:145], v[162:165], v[128:131]
	v_mfma_f32_16x16x32_bf16 v[124:127], v[150:153], v[162:165], v[124:127]
	v_mfma_f32_16x16x32_bf16 v[120:123], v[142:145], v[170:173], v[120:123]
	v_mfma_f32_16x16x32_bf16 v[116:119], v[150:153], v[170:173], v[116:119]
	v_mfma_f32_16x16x32_bf16 v[112:115], v[142:145], v[178:181], v[112:115]
	v_mfma_f32_16x16x32_bf16 v[108:111], v[150:153], v[178:181], v[108:111]
	v_mfma_f32_16x16x32_bf16 v[104:107], v[142:145], v[186:189], v[104:107]
	v_mfma_f32_16x16x32_bf16 v[100:103], v[150:153], v[186:189], v[100:103]
	v_mfma_f32_16x16x32_bf16 v[128:131], v[146:149], v[166:169], v[128:131]
	v_mfma_f32_16x16x32_bf16 v[124:127], v[158:161], v[166:169], v[124:127]
	v_mfma_f32_16x16x32_bf16 v[120:123], v[146:149], v[174:177], v[120:123]
	v_mfma_f32_16x16x32_bf16 v[116:119], v[158:161], v[174:177], v[116:119]
	v_mfma_f32_16x16x32_bf16 v[112:115], v[146:149], v[182:185], v[112:115]
	v_mfma_f32_16x16x32_bf16 v[108:111], v[158:161], v[182:185], v[108:111]
	v_mfma_f32_16x16x32_bf16 v[104:107], v[146:149], v[190:193], v[104:107]
	v_mfma_f32_16x16x32_bf16 v[100:103], v[158:161], v[190:193], v[100:103]
	v_mfma_f32_16x16x32_bf16 v[64:67], v[194:197], v[162:165], v[64:67]
	v_mfma_f32_16x16x32_bf16 v[60:63], v[202:205], v[162:165], v[60:63]
	v_mfma_f32_16x16x32_bf16 v[56:59], v[194:197], v[170:173], v[56:59]
	v_mfma_f32_16x16x32_bf16 v[52:55], v[202:205], v[170:173], v[52:55]
	v_mfma_f32_16x16x32_bf16 v[48:51], v[194:197], v[178:181], v[48:51]
	v_mfma_f32_16x16x32_bf16 v[44:47], v[202:205], v[178:181], v[44:47]
	v_mfma_f32_16x16x32_bf16 v[40:43], v[194:197], v[186:189], v[40:43]
	v_mfma_f32_16x16x32_bf16 v[36:39], v[202:205], v[186:189], v[36:39]
	v_mfma_f32_16x16x32_bf16 v[64:67], v[198:201], v[166:169], v[64:67]
	v_mfma_f32_16x16x32_bf16 v[60:63], v[206:209], v[166:169], v[60:63]
	v_mfma_f32_16x16x32_bf16 v[56:59], v[198:201], v[174:177], v[56:59]
	v_mfma_f32_16x16x32_bf16 v[52:55], v[206:209], v[174:177], v[52:55]
	v_mfma_f32_16x16x32_bf16 v[48:51], v[198:201], v[182:185], v[48:51]
	v_mfma_f32_16x16x32_bf16 v[44:47], v[206:209], v[182:185], v[44:47]
	v_mfma_f32_16x16x32_bf16 v[40:43], v[198:201], v[190:193], v[40:43]
	v_mfma_f32_16x16x32_bf16 v[36:39], v[206:209], v[190:193], v[36:39]
	s_barrier
	ds_read_b128 v[162:165], v156 offset:16384
	ds_read_b128 v[166:169], v156 offset:17408
	ds_read_b128 v[170:173], v156 offset:18432
	ds_read_b128 v[174:177], v156 offset:19456
	ds_read_b128 v[178:181], v156 offset:20480
	ds_read_b128 v[182:185], v156 offset:21504
	ds_read_b128 v[186:189], v156 offset:22528
	ds_read_b128 v[190:193], v156 offset:23552
	s_add_i32 s68, s68, s29
	v_lshl_add_u64 v[154:155], s[6:7], 0, v[2:3]
	s_mov_b32 m0, s68
	v_lshl_add_u64 v[210:211], s[6:7], 0, v[136:137]
	global_load_lds_dwordx4 v[154:155], off
	s_add_i32 m0, s68, 0x2000
	s_nop 0
	global_load_lds_dwordx4 v[210:211], off
	s_mov_b32 m0, s30
	v_lshl_add_u64 v[212:213], s[14:15], 0, v[132:133]
	global_load_lds_dwordx4 v[212:213], off
	v_lshl_add_u64 v[216:217], s[14:15], 0, v[134:135]
	s_mov_b32 m0, s31
	s_nop 0
	global_load_lds_dwordx4 v[216:217], off
	s_add_u32 s68, s6, 0x100000
	s_addc_u32 s69, s7, 0
	s_add_i32 s70, s70, s29
	s_mov_b32 m0, s70
	s_nop 0
	global_load_lds_dwordx4 v2, s[68:69]
	s_add_i32 m0, s70, 0x2000
	s_nop 0
	global_load_lds_dwordx4 v136, s[68:69]
	s_nop 0
	s_waitcnt lgkmcnt(0)
	s_waitcnt vmcnt(6)
	s_barrier
	v_mfma_f32_16x16x32_bf16 v[96:99], v[142:145], v[162:165], v[96:99]
	v_mfma_f32_16x16x32_bf16 v[92:95], v[150:153], v[162:165], v[92:95]
	v_mfma_f32_16x16x32_bf16 v[88:91], v[142:145], v[170:173], v[88:91]
	v_mfma_f32_16x16x32_bf16 v[84:87], v[150:153], v[170:173], v[84:87]
	v_mfma_f32_16x16x32_bf16 v[80:83], v[142:145], v[178:181], v[80:83]
	v_mfma_f32_16x16x32_bf16 v[76:79], v[150:153], v[178:181], v[76:79]
	v_mfma_f32_16x16x32_bf16 v[72:75], v[142:145], v[186:189], v[72:75]
	v_mfma_f32_16x16x32_bf16 v[68:71], v[150:153], v[186:189], v[68:71]
	v_mfma_f32_16x16x32_bf16 v[96:99], v[146:149], v[166:169], v[96:99]
	v_mfma_f32_16x16x32_bf16 v[92:95], v[158:161], v[166:169], v[92:95]
	v_mfma_f32_16x16x32_bf16 v[88:91], v[146:149], v[174:177], v[88:91]
	v_mfma_f32_16x16x32_bf16 v[84:87], v[158:161], v[174:177], v[84:87]
	v_mfma_f32_16x16x32_bf16 v[80:83], v[146:149], v[182:185], v[80:83]
	v_mfma_f32_16x16x32_bf16 v[76:79], v[158:161], v[182:185], v[76:79]
	v_mfma_f32_16x16x32_bf16 v[72:75], v[146:149], v[190:193], v[72:75]
	v_mfma_f32_16x16x32_bf16 v[68:71], v[158:161], v[190:193], v[68:71]
	v_mfma_f32_16x16x32_bf16 v[32:35], v[194:197], v[162:165], v[32:35]
	v_mfma_f32_16x16x32_bf16 v[28:31], v[202:205], v[162:165], v[28:31]
	v_mfma_f32_16x16x32_bf16 v[24:27], v[194:197], v[170:173], v[24:27]
	v_mfma_f32_16x16x32_bf16 v[20:23], v[202:205], v[170:173], v[20:23]
	v_mfma_f32_16x16x32_bf16 v[16:19], v[194:197], v[178:181], v[16:19]
	v_mfma_f32_16x16x32_bf16 v[12:15], v[202:205], v[178:181], v[12:15]
	v_mfma_f32_16x16x32_bf16 v[8:11], v[194:197], v[186:189], v[8:11]
	v_mfma_f32_16x16x32_bf16 v[4:7], v[202:205], v[186:189], v[4:7]
	v_mfma_f32_16x16x32_bf16 v[32:35], v[198:201], v[166:169], v[32:35]
	v_mfma_f32_16x16x32_bf16 v[28:31], v[206:209], v[166:169], v[28:31]
	v_mfma_f32_16x16x32_bf16 v[24:27], v[198:201], v[174:177], v[24:27]
	v_mfma_f32_16x16x32_bf16 v[20:23], v[206:209], v[174:177], v[20:23]
	v_mfma_f32_16x16x32_bf16 v[16:19], v[198:201], v[182:185], v[16:19]
	v_mfma_f32_16x16x32_bf16 v[12:15], v[206:209], v[182:185], v[12:15]
	v_mfma_f32_16x16x32_bf16 v[8:11], v[198:201], v[190:193], v[8:11]
	v_mfma_f32_16x16x32_bf16 v[4:7], v[206:209], v[190:193], v[4:7]
	s_barrier
; #define PG8_STAGE(bufoff, gbase, voff) do { _Pragma("unroll") for (int _i = 0; _i < 2; ++_i) \
;         __builtin_amdgcn_global_load_lds((const unsigned*)((const char*)(gbase) + (voff)[_i]), (LAS unsigned*)(lds + (bufoff) + ldsw + _i * 8192), 16, 0, 0); } while (0)
; #define PG8_LDA(dst, b, h) do { _Pragma("unroll") for (int m = 0; m < 4; ++m) _Pragma("unroll") for (int k = 0; k < 2; ++k) dst[m][k] = *(const LAS bf16x8*)(lds + PG8_SA(b, h) + aoff + m * 2048 + k * 1024); } while (0)
; #define PG8_LDB(dst, b, h) do { _Pragma("unroll") for (int n = 0; n < 2; ++n) _Pragma("unroll") for (int k = 0; k < 2; ++k) dst[n][k] = *(const LAS bf16x8*)(lds + PG8_SB(b, h) + boff + n * 2048 + k * 1024); } while (0)
; #define PG8_MMA(ai, bj, At, Bt) do { __builtin_amdgcn_s_setprio(1); _Pragma("unroll") for (int m = 0; m < 4; ++m) _Pragma("unroll") for (int n = 0; n < 2; ++n) _Pragma("unroll") for (int k = 0; k < 2; ++k) \
;         acc[ai][bj][m][n] = __builtin_amdgcn_mfma_f32_16x16x32_bf16(Bt[n][k], At[m][k], acc[ai][bj][m][n], 0, 0, 0); __builtin_amdgcn_s_setprio(0); } while (0)
; #define PG8_WAIT_L(n) asm volatile("s_waitcnt lgkmcnt(" #n ")" ::: "memory")
; #define PG8_BAR __builtin_amdgcn_s_barrier()
; #define PG8_SCHED __builtin_amdgcn_sched_barrier(0)
; template <class Epi, class Sched>
; __device__ __forceinline__ void gemm_phase(LAS unsigned char* lds, const Gemm g, const Sched& S, const Epi& E) {
;     ...
;             PG8_LDB(B0, 1, 0); PG8_SCHED; PG8_LDA(At, 1, 0); PG8_STAGE(PG8_SA(0, 1), a2 + hstepA, voffA);
;             PG8_WAIT_L(8); PG8_BAR; PG8_WAIT_L(0); PG8_MMA(0, 0, At, B0); PG8_BAR; PG8_SCHED;
;             PG8_LDB(B1, 1, 1); PG8_STAGE(PG8_SB(1, 0), b3, voffB);
;             PG8_BAR; PG8_WAIT_L(0); PG8_MMA(0, 1, At, B1); PG8_BAR;
	s_add_i32 s68, 0, 0x18000
	v_add_u32_e32 v157, s68, v1
	ds_read_b128 v[142:145], v157
	ds_read_b128 v[146:149], v157 offset:1024
	ds_read_b128 v[150:153], v157 offset:2048
	ds_read_b128 v[158:161], v157 offset:3072
	s_add_u32 s14, s14, 0x80000
	s_addc_u32 s15, s15, 0
	ds_read_b128 v[162:165], v156 offset:32768
	ds_read_b128 v[166:169], v156 offset:33792
	ds_read_b128 v[170:173], v156 offset:34816
	ds_read_b128 v[174:177], v156 offset:35840
	ds_read_b128 v[178:181], v156 offset:36864
	ds_read_b128 v[182:185], v156 offset:37888
	ds_read_b128 v[186:189], v156 offset:38912
	ds_read_b128 v[190:193], v156 offset:39936
	s_mov_b32 m0, s38
	s_nop 0
	global_load_lds_dwordx4 v132, s[14:15]
	s_mov_b32 m0, s39
	s_nop 0
	global_load_lds_dwordx4 v134, s[14:15]
	s_add_i32 s14, 0, 0x1c000
	v_add_u32_e32 v157, s14, v1
	ds_read_b128 v[194:197], v157
	ds_read_b128 v[198:201], v157 offset:1024
	ds_read_b128 v[202:205], v157 offset:2048
	ds_read_b128 v[206:209], v157 offset:3072
	s_waitcnt lgkmcnt(0)
	s_barrier
	v_mfma_f32_16x16x32_bf16 v[128:131], v[142:145], v[162:165], v[128:131]
	v_mfma_f32_16x16x32_bf16 v[124:127], v[150:153], v[162:165], v[124:127]
	v_mfma_f32_16x16x32_bf16 v[120:123], v[142:145], v[170:173], v[120:123]
	v_mfma_f32_16x16x32_bf16 v[116:119], v[150:153], v[170:173], v[116:119]
	v_mfma_f32_16x16x32_bf16 v[112:115], v[142:145], v[178:181], v[112:115]
	v_mfma_f32_16x16x32_bf16 v[108:111], v[150:153], v[178:181], v[108:111]
	v_mfma_f32_16x16x32_bf16 v[104:107], v[142:145], v[186:189], v[104:107]
	v_mfma_f32_16x16x32_bf16 v[100:103], v[150:153], v[186:189], v[100:103]
	v_mfma_f32_16x16x32_bf16 v[128:131], v[146:149], v[166:169], v[128:131]
	v_mfma_f32_16x16x32_bf16 v[124:127], v[158:161], v[166:169], v[124:127]
	v_mfma_f32_16x16x32_bf16 v[120:123], v[146:149], v[174:177], v[120:123]
	v_mfma_f32_16x16x32_bf16 v[116:119], v[158:161], v[174:177], v[116:119]
	v_mfma_f32_16x16x32_bf16 v[112:115], v[146:149], v[182:185], v[112:115]
	v_mfma_f32_16x16x32_bf16 v[108:111], v[158:161], v[182:185], v[108:111]
	v_mfma_f32_16x16x32_bf16 v[104:107], v[146:149], v[190:193], v[104:107]
	v_mfma_f32_16x16x32_bf16 v[100:103], v[158:161], v[190:193], v[100:103]
	v_mfma_f32_16x16x32_bf16 v[64:67], v[194:197], v[162:165], v[64:67]
	v_mfma_f32_16x16x32_bf16 v[60:63], v[202:205], v[162:165], v[60:63]
	v_mfma_f32_16x16x32_bf16 v[56:59], v[194:197], v[170:173], v[56:59]
	v_mfma_f32_16x16x32_bf16 v[52:55], v[202:205], v[170:173], v[52:55]
	v_mfma_f32_16x16x32_bf16 v[48:51], v[194:197], v[178:181], v[48:51]
	v_mfma_f32_16x16x32_bf16 v[44:47], v[202:205], v[178:181], v[44:47]
	v_mfma_f32_16x16x32_bf16 v[40:43], v[194:197], v[186:189], v[40:43]
	v_mfma_f32_16x16x32_bf16 v[36:39], v[202:205], v[186:189], v[36:39]
	v_mfma_f32_16x16x32_bf16 v[64:67], v[198:201], v[166:169], v[64:67]
	v_mfma_f32_16x16x32_bf16 v[60:63], v[206:209], v[166:169], v[60:63]
	v_mfma_f32_16x16x32_bf16 v[56:59], v[198:201], v[174:177], v[56:59]
	v_mfma_f32_16x16x32_bf16 v[52:55], v[206:209], v[174:177], v[52:55]
	v_mfma_f32_16x16x32_bf16 v[48:51], v[198:201], v[182:185], v[48:51]
	v_mfma_f32_16x16x32_bf16 v[44:47], v[206:209], v[182:185], v[44:47]
	v_mfma_f32_16x16x32_bf16 v[40:43], v[198:201], v[190:193], v[40:43]
	v_mfma_f32_16x16x32_bf16 v[36:39], v[206:209], v[190:193], v[36:39]
	s_barrier
; __device__ __forceinline__ int opaque_tid() { int t = threadIdx.x; asm volatile("" : "+v"(t)); return t; }
; #define PG8_STAGE(bufoff, gbase, voff) do { _Pragma("unroll") for (int _i = 0; _i < 2; ++_i) \
;         __builtin_amdgcn_global_load_lds((const unsigned*)((const char*)(gbase) + (voff)[_i]), (LAS unsigned*)(lds + (bufoff) + ldsw + _i * 8192), 16, 0, 0); } while (0)
; #define PG8_LDA(dst, b, h) do { _Pragma("unroll") for (int m = 0; m < 4; ++m) _Pragma("unroll") for (int k = 0; k < 2; ++k) dst[m][k] = *(const LAS bf16x8*)(lds + PG8_SA(b, h) + aoff + m * 2048 + k * 1024); } while (0)
; #define PG8_MMA(ai, bj, At, Bt) do { __builtin_amdgcn_s_setprio(1); _Pragma("unroll") for (int m = 0; m < 4; ++m) _Pragma("unroll") for (int n = 0; n < 2; ++n) _Pragma("unroll") for (int k = 0; k < 2; ++k) \
;         acc[ai][bj][m][n] = __builtin_amdgcn_mfma_f32_16x16x32_bf16(Bt[n][k], At[m][k], acc[ai][bj][m][n], 0, 0, 0); __builtin_amdgcn_s_setprio(0); } while (0)
; #define PG8_WAIT_V(n) asm volatile("s_waitcnt vmcnt(" #n ")" ::: "memory")
; #define PG8_WAIT_L(n) asm volatile("s_waitcnt lgkmcnt(" #n ")" ::: "memory")
; #define PG8_BAR __builtin_amdgcn_s_barrier()
; #define PG8_SCHED __builtin_amdgcn_sched_barrier(0)
; template <class Epi, class Sched>
; __device__ __forceinline__ void gemm_phase(LAS unsigned char* lds, const Gemm g, const Sched& S, const Epi& E) {
;     ...
;             PG8_LDA(At, 1, 1); PG8_STAGE(PG8_SA(1, 0), a3, voffA);
;             PG8_BAR; PG8_WAIT_L(0); PG8_MMA(1, 0, At, B0); PG8_BAR; PG8_SCHED;
;             PG8_STAGE(PG8_SB(1, 1), b3 + hstepB, voffB);
;             PG8_WAIT_V(6); PG8_BAR; PG8_MMA(1, 1, At, B1); PG8_BAR;
;         }
;     __device__ __forceinline__ void operator()(const f32x4 (&acc)[2][2][4][2], const Unit& u, int wr, int wc, int, int) const {
;         const int ol_ = opaque_tid() & 63, fr = ol_ & 15, fq = ol_ >> 4;
;         const int row0 = u.pm * BM + wr * 64 + fr, col0 = u.pn * BM + wc * 32 + 8 * fq;
; #pragma unroll
;         for (int bj = 0; bj < 2; ++bj) { f32x4 b0 = (f32x4){0.f, 0.f, 0.f, 0.f}, b1 = b0;
; #pragma unroll 8
;             for (int pp = 0; pp < 32; ++pp) { b0 += *(const f32x4*)(bias + pp * 256 + col0 + bj * HALF); b1 += *(const f32x4*)(bias + pp * 256 + col0 + bj * HALF + 4); }
	ds_read_b128 v[162:165], v156 offset:49152
	ds_read_b128 v[166:169], v156 offset:50176
	ds_read_b128 v[170:173], v156 offset:51200
	ds_read_b128 v[174:177], v156 offset:52224
	ds_read_b128 v[178:181], v156 offset:53248
	ds_read_b128 v[182:185], v156 offset:54272
	ds_read_b128 v[186:189], v156 offset:55296
	ds_read_b128 v[190:193], v156 offset:56320
	s_add_i32 s15, s68, s29
	v_lshl_add_u64 v[154:155], v[154:155], 0, s[8:9]
	s_mov_b32 m0, s15
	s_nop 0
	global_load_lds_dwordx4 v[154:155], off
	v_lshl_add_u64 v[154:155], v[210:211], 0, s[8:9]
	s_add_i32 m0, s15, 0x2000
	s_nop 0
	global_load_lds_dwordx4 v[154:155], off
	s_mov_b32 m0, s62
	v_lshl_add_u64 v[154:155], v[212:213], 0, s[8:9]
	global_load_lds_dwordx4 v[154:155], off
	v_lshl_add_u64 v[154:155], v[216:217], 0, s[8:9]
	s_mov_b32 m0, s63
	s_nop 0
	global_load_lds_dwordx4 v[154:155], off
	s_add_u32 s6, s6, 0x100080
	s_addc_u32 s7, s7, 0
	s_add_i32 s14, s14, s29
	s_mov_b32 m0, s14
	s_nop 0
	global_load_lds_dwordx4 v2, s[6:7]
	s_add_i32 m0, s14, 0x2000
	s_nop 0
	global_load_lds_dwordx4 v136, s[6:7]
	s_add_i32 s67, s67, 2
	s_add_u32 s4, s4, 0x100
	s_addc_u32 s5, s5, 0
	s_add_u32 s65, s65, 0x100
	s_addc_u32 s66, s66, 0
	s_cmp_gt_u32 s67, 61
	s_waitcnt lgkmcnt(0)
	s_waitcnt vmcnt(6)
	s_barrier
	v_mfma_f32_16x16x32_bf16 v[96:99], v[142:145], v[162:165], v[96:99]
	v_mfma_f32_16x16x32_bf16 v[92:95], v[150:153], v[162:165], v[92:95]
	v_mfma_f32_16x16x32_bf16 v[88:91], v[142:145], v[170:173], v[88:91]
	v_mfma_f32_16x16x32_bf16 v[84:87], v[150:153], v[170:173], v[84:87]
	v_mfma_f32_16x16x32_bf16 v[80:83], v[142:145], v[178:181], v[80:83]
	v_mfma_f32_16x16x32_bf16 v[76:79], v[150:153], v[178:181], v[76:79]
	v_mfma_f32_16x16x32_bf16 v[72:75], v[142:145], v[186:189], v[72:75]
	v_mfma_f32_16x16x32_bf16 v[68:71], v[150:153], v[186:189], v[68:71]
	v_mfma_f32_16x16x32_bf16 v[96:99], v[146:149], v[166:169], v[96:99]
	v_mfma_f32_16x16x32_bf16 v[92:95], v[158:161], v[166:169], v[92:95]
	v_mfma_f32_16x16x32_bf16 v[88:91], v[146:149], v[174:177], v[88:91]
	v_mfma_f32_16x16x32_bf16 v[84:87], v[158:161], v[174:177], v[84:87]
	v_mfma_f32_16x16x32_bf16 v[80:83], v[146:149], v[182:185], v[80:83]
	v_mfma_f32_16x16x32_bf16 v[76:79], v[158:161], v[182:185], v[76:79]
	v_mfma_f32_16x16x32_bf16 v[72:75], v[146:149], v[190:193], v[72:75]
	v_mfma_f32_16x16x32_bf16 v[68:71], v[158:161], v[190:193], v[68:71]
	v_mfma_f32_16x16x32_bf16 v[32:35], v[194:197], v[162:165], v[32:35]
	v_mfma_f32_16x16x32_bf16 v[28:31], v[202:205], v[162:165], v[28:31]
	v_mfma_f32_16x16x32_bf16 v[24:27], v[194:197], v[170:173], v[24:27]
	v_mfma_f32_16x16x32_bf16 v[20:23], v[202:205], v[170:173], v[20:23]
	v_mfma_f32_16x16x32_bf16 v[16:19], v[194:197], v[178:181], v[16:19]
	v_mfma_f32_16x16x32_bf16 v[12:15], v[202:205], v[178:181], v[12:15]
	v_mfma_f32_16x16x32_bf16 v[8:11], v[194:197], v[186:189], v[8:11]
	v_mfma_f32_16x16x32_bf16 v[4:7], v[202:205], v[186:189], v[4:7]
	v_mfma_f32_16x16x32_bf16 v[32:35], v[198:201], v[166:169], v[32:35]
	v_mfma_f32_16x16x32_bf16 v[28:31], v[206:209], v[166:169], v[28:31]
	v_mfma_f32_16x16x32_bf16 v[24:27], v[198:201], v[174:177], v[24:27]
	v_mfma_f32_16x16x32_bf16 v[20:23], v[206:209], v[174:177], v[20:23]
	v_mfma_f32_16x16x32_bf16 v[16:19], v[198:201], v[182:185], v[16:19]
	v_mfma_f32_16x16x32_bf16 v[12:15], v[206:209], v[182:185], v[12:15]
	v_mfma_f32_16x16x32_bf16 v[8:11], v[198:201], v[190:193], v[8:11]
	v_mfma_f32_16x16x32_bf16 v[4:7], v[206:209], v[190:193], v[4:7]
	s_barrier
	s_cbranch_scc0 .LBB0_491
	v_mov_b32_e32 v157, v0
	s_lshl_b32 s1, s1, 8
	v_lshrrev_b32_e32 v142, 1, v157
	v_and_or_b32 v142, v142, 24, s1
	v_or_b32_e32 v154, s61, v142
	v_ashrrev_i32_e32 v155, 31, v154
	v_mov_b32_e32 v144, 0
	v_lshl_add_u64 v[142:143], v[154:155], 2, s[46:47]
	s_mov_b64 s[4:5], 0
	v_mov_b32_e32 v145, v144
	v_mov_b32_e32 v146, v144
	v_mov_b32_e32 v147, v144
	v_mov_b32_e32 v148, v144
	v_mov_b32_e32 v149, v144
	v_mov_b32_e32 v150, v144
	v_mov_b32_e32 v151, v144

;     __device__ __forceinline__ void prefetch(const Unit& u, int ui) const { if (rs) rs_prefetch(rs, u.pm, ui); }
;     __device__ __forceinline__ void prefetch(const Unit& u, int ui) const { rs_prefetch(rs, u.pm, ui); }
; #define PG8_STAGE(bufoff, gbase, voff) do { _Pragma("unroll") for (int _i = 0; _i < 2; ++_i) \
;         __builtin_amdgcn_global_load_lds((const unsigned*)((const char*)(gbase) + (voff)[_i]), (LAS unsigned*)(lds + (bufoff) + ldsw + _i * 8192), 16, 0, 0); } while (0)
; #define PG8_LDA(dst, b, h) do { _Pragma("unroll") for (int m = 0; m < 4; ++m) _Pragma("unroll") for (int k = 0; k < 2; ++k) dst[m][k] = *(const LAS bf16x8*)(lds + PG8_SA(b, h) + aoff + m * 2048 + k * 1024); } while (0)
; #define PG8_LDB(dst, b, h) do { _Pragma("unroll") for (int n = 0; n < 2; ++n) _Pragma("unroll") for (int k = 0; k < 2; ++k) dst[n][k] = *(const LAS bf16x8*)(lds + PG8_SB(b, h) + boff + n * 2048 + k * 1024); } while (0)
; template <class Epi, class Sched>
; __device__ __forceinline__ void gemm_phase(LAS unsigned char* lds, const Gemm g, const Sched& S, const Epi& E) {
;     ...
;     for (;;) {
;         E.prefetch(cur, ui);
;         const bool has_next = S.next(ui + 1, nxt);
;         const char* nA = has_next ? (const char*)g.A + (size_t)nxt.pm * tstepA : cA; const char* nB = has_next ? (const char*)g.Bt + (size_t)nxt.pn * tstepB : cB;
;         for (int t = 0; t < nt; t += 2) {
;             const bool last = (t == nt - 2);
;             const char* a1 = cA + (size_t)(t + 1) * kstep;
;             const char* a2 = last ? nA : cA + (size_t)(t + 2) * kstep; const char* b2 = last ? nB : cB + (size_t)(t + 2) * kstep;
;             const char* a3 = a2 + kstep; const char* b3 = b2 + kstep;
;             if (last && has_next) S.a_ready(nxt);
;             PG8_LDB(B0, 0, 0); PG8_SCHED; PG8_LDA(At, 0, 0); PG8_STAGE(PG8_SA(1, 1), a1 + hstepA, voffA);
;             PG8_WAIT_L(8); PG8_BAR; PG8_WAIT_L(0); PG8_MMA(0, 0, At, B0); PG8_BAR; PG8_SCHED;
;             PG8_LDB(B1, 0, 1); PG8_STAGE(PG8_SB(0, 0), b2, voffB);
;             PG8_BAR; PG8_WAIT_L(0); PG8_MMA(0, 1, At, B1); PG8_BAR;
;             PG8_LDA(At, 0, 1); PG8_STAGE(PG8_SA(0, 0), a2, voffA);
;             PG8_BAR; PG8_WAIT_L(0); PG8_MMA(1, 0, At, B0); PG8_BAR; PG8_SCHED;
;             PG8_STAGE(PG8_SB(0, 1), b2 + hstepB, voffB);
;             PG8_WAIT_V(6); PG8_BAR; PG8_MMA(1, 1, At, B1); PG8_BAR;
.LBB0_1093:
	v_mov_b64_e32 v[4:5], 0x900
	s_ashr_i32 s5, s4, 31
	v_cmp_lt_i64_e32 vcc, s[6:7], v[4:5]
	s_lshl_b64 s[6:7], s[4:5], 20
	s_add_u32 s6, s88, s6
	s_addc_u32 s7, s89, s7
	s_and_b64 s[14:15], vcc, exec
	s_cselect_b32 s5, s7, s19
	s_cselect_b32 s49, s6, s18
	s_ashr_i32 s1, s0, 31
	s_lshl_b64 s[14:15], s[0:1], 20
	s_add_u32 s14, s28, s14
	s_addc_u32 s15, s29, s15
	s_and_b64 s[24:25], vcc, exec
	s_cselect_b32 s1, s15, s21
	s_cselect_b32 s50, s14, s20
	s_add_u32 s18, s18, 0x80080
	s_addc_u32 s19, s19, 0
	s_add_u32 s51, s20, 0x100
	s_addc_u32 s52, s21, 0
	s_mov_b32 s53, -2
	s_add_u32 s20, s18, 0xfff80080
	s_addc_u32 s21, s19, -1
	s_add_i32 s54, 0, 0x10000
	v_add_u32_e32 v146, s54, v1
	ds_read_b128 v[142:145], v146
	ds_read_b128 v[150:153], v146 offset:1024
	ds_read_b128 v[154:157], v146 offset:2048
	ds_read_b128 v[158:161], v146 offset:3072
	s_cmp_eq_u32 s53, 28
	s_cselect_b32 s25, s5, s21
	s_cselect_b32 s24, s49, s20
	s_cselect_b32 s21, s1, s52
	s_cselect_b32 s20, s50, s51
	ds_read_b128 v[162:165], v148
	ds_read_b128 v[166:169], v148 offset:1024
	ds_read_b128 v[170:173], v148 offset:2048
	ds_read_b128 v[174:177], v148 offset:3072
	ds_read_b128 v[178:181], v148 offset:4096
	ds_read_b128 v[182:185], v148 offset:5120
	ds_read_b128 v[186:189], v148 offset:6144
	ds_read_b128 v[190:193], v148 offset:7168
	s_add_i32 s56, 0, 0x14000
	v_add_u32_e32 v146, s56, v1
	ds_read_b128 v[194:197], v146
	ds_read_b128 v[198:201], v146 offset:1024
	ds_read_b128 v[202:205], v146 offset:2048
	ds_read_b128 v[206:209], v146 offset:3072
	s_add_i32 m0, s31, 0xc000
	s_nop 0
	global_load_lds_dwordx4 v138, s[18:19]
	s_add_i32 m0, s31, 0xe000
	s_nop 0
	global_load_lds_dwordx4 v140, s[18:19]
	s_waitcnt lgkmcnt(0)
	s_barrier
	v_mfma_f32_16x16x32_bf16 v[128:131], v[142:145], v[162:165], 0
	v_mfma_f32_16x16x32_bf16 v[124:127], v[154:157], v[162:165], 0
	v_mfma_f32_16x16x32_bf16 v[120:123], v[142:145], v[170:173], 0
	v_mfma_f32_16x16x32_bf16 v[112:115], v[154:157], v[170:173], 0
	v_mfma_f32_16x16x32_bf16 v[104:107], v[142:145], v[178:181], 0
	v_mfma_f32_16x16x32_bf16 v[96:99], v[154:157], v[178:181], 0
	v_mfma_f32_16x16x32_bf16 v[88:91], v[142:145], v[186:189], 0
	v_mfma_f32_16x16x32_bf16 v[80:83], v[154:157], v[186:189], 0
	v_mfma_f32_16x16x32_bf16 v[128:131], v[150:153], v[166:169], v[128:131]
	v_mfma_f32_16x16x32_bf16 v[124:127], v[158:161], v[166:169], v[124:127]
	v_mfma_f32_16x16x32_bf16 v[120:123], v[150:153], v[174:177], v[120:123]
	v_mfma_f32_16x16x32_bf16 v[112:115], v[158:161], v[174:177], v[112:115]
	v_mfma_f32_16x16x32_bf16 v[104:107], v[150:153], v[182:185], v[104:107]
	v_mfma_f32_16x16x32_bf16 v[96:99], v[158:161], v[182:185], v[96:99]
	v_mfma_f32_16x16x32_bf16 v[88:91], v[150:153], v[190:193], v[88:91]
	v_mfma_f32_16x16x32_bf16 v[80:83], v[158:161], v[190:193], v[80:83]
	v_mfma_f32_16x16x32_bf16 v[116:119], v[194:197], v[162:165], 0
	v_mfma_f32_16x16x32_bf16 v[108:111], v[202:205], v[162:165], 0
	v_mfma_f32_16x16x32_bf16 v[100:103], v[194:197], v[170:173], 0
	v_mfma_f32_16x16x32_bf16 v[92:95], v[202:205], v[170:173], 0
	v_mfma_f32_16x16x32_bf16 v[84:87], v[194:197], v[178:181], 0
	v_mfma_f32_16x16x32_bf16 v[76:79], v[202:205], v[178:181], 0
	v_mfma_f32_16x16x32_bf16 v[72:75], v[194:197], v[186:189], 0
	v_mfma_f32_16x16x32_bf16 v[68:71], v[202:205], v[186:189], 0
	v_mfma_f32_16x16x32_bf16 v[116:119], v[198:201], v[166:169], v[116:119]
	v_mfma_f32_16x16x32_bf16 v[108:111], v[206:209], v[166:169], v[108:111]
	v_mfma_f32_16x16x32_bf16 v[100:103], v[198:201], v[174:177], v[100:103]
	v_mfma_f32_16x16x32_bf16 v[92:95], v[206:209], v[174:177], v[92:95]
	v_mfma_f32_16x16x32_bf16 v[84:87], v[198:201], v[182:185], v[84:87]
	v_mfma_f32_16x16x32_bf16 v[76:79], v[206:209], v[182:185], v[76:79]
	v_mfma_f32_16x16x32_bf16 v[72:75], v[198:201], v[190:193], v[72:75]
	v_mfma_f32_16x16x32_bf16 v[68:71], v[206:209], v[190:193], v[68:71]
	s_barrier
	ds_read_b128 v[162:165], v148 offset:16384
	ds_read_b128 v[166:169], v148 offset:17408
	ds_read_b128 v[170:173], v148 offset:18432
	ds_read_b128 v[174:177], v148 offset:19456
	ds_read_b128 v[178:181], v148 offset:20480
	ds_read_b128 v[182:185], v148 offset:21504
	ds_read_b128 v[186:189], v148 offset:22528
	ds_read_b128 v[190:193], v148 offset:23552
	s_add_i32 s54, s54, s30
	v_lshl_add_u64 v[146:147], s[20:21], 0, v[2:3]
	s_mov_b32 m0, s54
	v_lshl_add_u64 v[210:211], s[20:21], 0, v[132:133]
	global_load_lds_dwordx4 v[146:147], off
	s_add_i32 m0, s54, 0x2000
	s_nop 0
	global_load_lds_dwordx4 v[210:211], off
	s_mov_b32 m0, s31
	v_lshl_add_u64 v[212:213], s[24:25], 0, v[136:137]
	global_load_lds_dwordx4 v[212:213], off
	v_lshl_add_u64 v[216:217], s[24:25], 0, v[134:135]
	s_mov_b32 m0, s35
	s_nop 0
	global_load_lds_dwordx4 v[216:217], off
	s_add_u32 s54, s20, 0x80000
	s_addc_u32 s55, s21, 0
	s_add_i32 s56, s56, s30
	s_mov_b32 m0, s56
	s_nop 0
	global_load_lds_dwordx4 v2, s[54:55]
	s_add_i32 m0, s56, 0x2000
	s_nop 0
	global_load_lds_dwordx4 v132, s[54:55]
	s_nop 0
	s_waitcnt lgkmcnt(0)
	s_waitcnt vmcnt(6)
	s_barrier
; #define PG8_STAGE(bufoff, gbase, voff) do { _Pragma("unroll") for (int _i = 0; _i < 2; ++_i) \
;         __builtin_amdgcn_global_load_lds((const unsigned*)((const char*)(gbase) + (voff)[_i]), (LAS unsigned*)(lds + (bufoff) + ldsw + _i * 8192), 16, 0, 0); } while (0)
; #define PG8_LDA(dst, b, h) do { _Pragma("unroll") for (int m = 0; m < 4; ++m) _Pragma("unroll") for (int k = 0; k < 2; ++k) dst[m][k] = *(const LAS bf16x8*)(lds + PG8_SA(b, h) + aoff + m * 2048 + k * 1024); } while (0)
; #define PG8_LDB(dst, b, h) do { _Pragma("unroll") for (int n = 0; n < 2; ++n) _Pragma("unroll") for (int k = 0; k < 2; ++k) dst[n][k] = *(const LAS bf16x8*)(lds + PG8_SB(b, h) + boff + n * 2048 + k * 1024); } while (0)
; #define PG8_MMA(ai, bj, At, Bt) do { __builtin_amdgcn_s_setprio(1); _Pragma("unroll") for (int m = 0; m < 4; ++m) _Pragma("unroll") for (int n = 0; n < 2; ++n) _Pragma("unroll") for (int k = 0; k < 2; ++k) \
;         acc[ai][bj][m][n] = __builtin_amdgcn_mfma_f32_16x16x32_bf16(Bt[n][k], At[m][k], acc[ai][bj][m][n], 0, 0, 0); __builtin_amdgcn_s_setprio(0); } while (0)
; #define PG8_WAIT_V(n) asm volatile("s_waitcnt vmcnt(" #n ")" ::: "memory")
; #define PG8_WAIT_L(n) asm volatile("s_waitcnt lgkmcnt(" #n ")" ::: "memory")
; #define PG8_BAR __builtin_amdgcn_s_barrier()
; #define PG8_SCHED __builtin_amdgcn_sched_barrier(0)
; template <class Epi, class Sched>
; __device__ __forceinline__ void gemm_phase(LAS unsigned char* lds, const Gemm g, const Sched& S, const Epi& E) {
;     ...
;             PG8_BAR; PG8_WAIT_L(0); PG8_MMA(1, 0, At, B0); PG8_BAR; PG8_SCHED;
;             PG8_STAGE(PG8_SB(0, 1), b2 + hstepB, voffB);
;             PG8_WAIT_V(6); PG8_BAR; PG8_MMA(1, 1, At, B1); PG8_BAR;
;             PG8_LDB(B0, 1, 0); PG8_SCHED; PG8_LDA(At, 1, 0); PG8_STAGE(PG8_SA(0, 1), a2 + hstepA, voffA);
;             PG8_WAIT_L(8); PG8_BAR; PG8_WAIT_L(0); PG8_MMA(0, 0, At, B0); PG8_BAR; PG8_SCHED;
;             PG8_LDB(B1, 1, 1); PG8_STAGE(PG8_SB(1, 0), b3, voffB);
;             PG8_BAR; PG8_WAIT_L(0); PG8_MMA(0, 1, At, B1); PG8_BAR;
	v_mfma_f32_16x16x32_bf16 v[64:67], v[142:145], v[162:165], 0
	v_mfma_f32_16x16x32_bf16 v[60:63], v[154:157], v[162:165], 0
	v_mfma_f32_16x16x32_bf16 v[56:59], v[142:145], v[170:173], 0
	v_mfma_f32_16x16x32_bf16 v[48:51], v[154:157], v[170:173], 0
	v_mfma_f32_16x16x32_bf16 v[40:43], v[142:145], v[178:181], 0
	v_mfma_f32_16x16x32_bf16 v[32:35], v[154:157], v[178:181], 0
	v_mfma_f32_16x16x32_bf16 v[24:27], v[142:145], v[186:189], 0
	v_mfma_f32_16x16x32_bf16 v[16:19], v[154:157], v[186:189], 0
	v_mfma_f32_16x16x32_bf16 v[64:67], v[150:153], v[166:169], v[64:67]
	v_mfma_f32_16x16x32_bf16 v[60:63], v[158:161], v[166:169], v[60:63]
	v_mfma_f32_16x16x32_bf16 v[56:59], v[150:153], v[174:177], v[56:59]
	v_mfma_f32_16x16x32_bf16 v[48:51], v[158:161], v[174:177], v[48:51]
	v_mfma_f32_16x16x32_bf16 v[40:43], v[150:153], v[182:185], v[40:43]
	v_mfma_f32_16x16x32_bf16 v[32:35], v[158:161], v[182:185], v[32:35]
	v_mfma_f32_16x16x32_bf16 v[24:27], v[150:153], v[190:193], v[24:27]
	v_mfma_f32_16x16x32_bf16 v[16:19], v[158:161], v[190:193], v[16:19]
	v_mfma_f32_16x16x32_bf16 v[52:55], v[194:197], v[162:165], 0
	v_mfma_f32_16x16x32_bf16 v[44:47], v[202:205], v[162:165], 0
	v_mfma_f32_16x16x32_bf16 v[36:39], v[194:197], v[170:173], 0
	v_mfma_f32_16x16x32_bf16 v[28:31], v[202:205], v[170:173], 0
	v_mfma_f32_16x16x32_bf16 v[20:23], v[194:197], v[178:181], 0
	v_mfma_f32_16x16x32_bf16 v[12:15], v[202:205], v[178:181], 0
	v_mfma_f32_16x16x32_bf16 v[8:11], v[194:197], v[186:189], 0
	v_mfma_f32_16x16x32_bf16 v[4:7], v[202:205], v[186:189], 0
	v_mfma_f32_16x16x32_bf16 v[52:55], v[198:201], v[166:169], v[52:55]
	v_mfma_f32_16x16x32_bf16 v[44:47], v[206:209], v[166:169], v[44:47]
	v_mfma_f32_16x16x32_bf16 v[36:39], v[198:201], v[174:177], v[36:39]
	v_mfma_f32_16x16x32_bf16 v[28:31], v[206:209], v[174:177], v[28:31]
	v_mfma_f32_16x16x32_bf16 v[20:23], v[198:201], v[182:185], v[20:23]
	v_mfma_f32_16x16x32_bf16 v[12:15], v[206:209], v[182:185], v[12:15]
	v_mfma_f32_16x16x32_bf16 v[8:11], v[198:201], v[190:193], v[8:11]
	v_mfma_f32_16x16x32_bf16 v[4:7], v[206:209], v[190:193], v[4:7]
	s_barrier
	s_add_i32 s54, 0, 0x18000
	v_add_u32_e32 v149, s54, v1
	ds_read_b128 v[142:145], v149
	ds_read_b128 v[150:153], v149 offset:1024
	ds_read_b128 v[154:157], v149 offset:2048
	ds_read_b128 v[158:161], v149 offset:3072
	s_add_u32 s24, s24, 0x80000
	s_addc_u32 s25, s25, 0
	ds_read_b128 v[162:165], v148 offset:32768
	ds_read_b128 v[166:169], v148 offset:33792
	ds_read_b128 v[170:173], v148 offset:34816
	ds_read_b128 v[174:177], v148 offset:35840
	ds_read_b128 v[178:181], v148 offset:36864
	ds_read_b128 v[182:185], v148 offset:37888
	ds_read_b128 v[186:189], v148 offset:38912
	ds_read_b128 v[190:193], v148 offset:39936
	s_mov_b32 m0, s36
	s_nop 0
	global_load_lds_dwordx4 v136, s[24:25]
	s_mov_b32 m0, s37
	s_nop 0
	global_load_lds_dwordx4 v134, s[24:25]
	s_add_i32 s24, 0, 0x1c000
	v_add_u32_e32 v149, s24, v1
	ds_read_b128 v[194:197], v149
	ds_read_b128 v[198:201], v149 offset:1024
	ds_read_b128 v[202:205], v149 offset:2048
	ds_read_b128 v[206:209], v149 offset:3072
	s_waitcnt lgkmcnt(0)
	s_barrier
	v_mfma_f32_16x16x32_bf16 v[128:131], v[142:145], v[162:165], v[128:131]
	v_mfma_f32_16x16x32_bf16 v[124:127], v[154:157], v[162:165], v[124:127]
	v_mfma_f32_16x16x32_bf16 v[120:123], v[142:145], v[170:173], v[120:123]
	v_mfma_f32_16x16x32_bf16 v[112:115], v[154:157], v[170:173], v[112:115]
	v_mfma_f32_16x16x32_bf16 v[104:107], v[142:145], v[178:181], v[104:107]
	v_mfma_f32_16x16x32_bf16 v[96:99], v[154:157], v[178:181], v[96:99]
	v_mfma_f32_16x16x32_bf16 v[88:91], v[142:145], v[186:189], v[88:91]
	v_mfma_f32_16x16x32_bf16 v[80:83], v[154:157], v[186:189], v[80:83]
	v_mfma_f32_16x16x32_bf16 v[128:131], v[150:153], v[166:169], v[128:131]
	v_mfma_f32_16x16x32_bf16 v[124:127], v[158:161], v[166:169], v[124:127]
	v_mfma_f32_16x16x32_bf16 v[120:123], v[150:153], v[174:177], v[120:123]
	v_mfma_f32_16x16x32_bf16 v[112:115], v[158:161], v[174:177], v[112:115]
	v_mfma_f32_16x16x32_bf16 v[104:107], v[150:153], v[182:185], v[104:107]
	v_mfma_f32_16x16x32_bf16 v[96:99], v[158:161], v[182:185], v[96:99]
	v_mfma_f32_16x16x32_bf16 v[88:91], v[150:153], v[190:193], v[88:91]
	v_mfma_f32_16x16x32_bf16 v[80:83], v[158:161], v[190:193], v[80:83]
	v_mfma_f32_16x16x32_bf16 v[116:119], v[194:197], v[162:165], v[116:119]
	v_mfma_f32_16x16x32_bf16 v[108:111], v[202:205], v[162:165], v[108:111]
	v_mfma_f32_16x16x32_bf16 v[100:103], v[194:197], v[170:173], v[100:103]
	v_mfma_f32_16x16x32_bf16 v[92:95], v[202:205], v[170:173], v[92:95]
	v_mfma_f32_16x16x32_bf16 v[84:87], v[194:197], v[178:181], v[84:87]
	v_mfma_f32_16x16x32_bf16 v[76:79], v[202:205], v[178:181], v[76:79]
	v_mfma_f32_16x16x32_bf16 v[72:75], v[194:197], v[186:189], v[72:75]
	v_mfma_f32_16x16x32_bf16 v[68:71], v[202:205], v[186:189], v[68:71]
	v_mfma_f32_16x16x32_bf16 v[116:119], v[198:201], v[166:169], v[116:119]
	v_mfma_f32_16x16x32_bf16 v[108:111], v[206:209], v[166:169], v[108:111]
	v_mfma_f32_16x16x32_bf16 v[100:103], v[198:201], v[174:177], v[100:103]
	v_mfma_f32_16x16x32_bf16 v[92:95], v[206:209], v[174:177], v[92:95]
	v_mfma_f32_16x16x32_bf16 v[84:87], v[198:201], v[182:185], v[84:87]
	v_mfma_f32_16x16x32_bf16 v[76:79], v[206:209], v[182:185], v[76:79]
	v_mfma_f32_16x16x32_bf16 v[72:75], v[198:201], v[190:193], v[72:75]
	v_mfma_f32_16x16x32_bf16 v[68:71], v[206:209], v[190:193], v[68:71]
	s_barrier
; #define PG8_STAGE(bufoff, gbase, voff) do { _Pragma("unroll") for (int _i = 0; _i < 2; ++_i) \
;         __builtin_amdgcn_global_load_lds((const unsigned*)((const char*)(gbase) + (voff)[_i]), (LAS unsigned*)(lds + (bufoff) + ldsw + _i * 8192), 16, 0, 0); } while (0)
; #define PG8_LDA(dst, b, h) do { _Pragma("unroll") for (int m = 0; m < 4; ++m) _Pragma("unroll") for (int k = 0; k < 2; ++k) dst[m][k] = *(const LAS bf16x8*)(lds + PG8_SA(b, h) + aoff + m * 2048 + k * 1024); } while (0)
; #define PG8_LDB(dst, b, h) do { _Pragma("unroll") for (int n = 0; n < 2; ++n) _Pragma("unroll") for (int k = 0; k < 2; ++k) dst[n][k] = *(const LAS bf16x8*)(lds + PG8_SB(b, h) + boff + n * 2048 + k * 1024); } while (0)
; #define PG8_MMA(ai, bj, At, Bt) do { __builtin_amdgcn_s_setprio(1); _Pragma("unroll") for (int m = 0; m < 4; ++m) _Pragma("unroll") for (int n = 0; n < 2; ++n) _Pragma("unroll") for (int k = 0; k < 2; ++k) \
;         acc[ai][bj][m][n] = __builtin_amdgcn_mfma_f32_16x16x32_bf16(Bt[n][k], At[m][k], acc[ai][bj][m][n], 0, 0, 0); __builtin_amdgcn_s_setprio(0); } while (0)
; #define PG8_WAIT_V(n) asm volatile("s_waitcnt vmcnt(" #n ")" ::: "memory")
; #define PG8_WAIT_L(n) asm volatile("s_waitcnt lgkmcnt(" #n ")" ::: "memory")
; #define PG8_BAR __builtin_amdgcn_s_barrier()
; #define PG8_SCHED __builtin_amdgcn_sched_barrier(0)
; template <class Epi, class Sched>
; __device__ __forceinline__ void gemm_phase(LAS unsigned char* lds, const Gemm g, const Sched& S, const Epi& E) {
;     ...
;         for (int t = 0; t < nt; t += 2) {
;             const bool last = (t == nt - 2);
;             const char* a1 = cA + (size_t)(t + 1) * kstep;
;             const char* a2 = last ? nA : cA + (size_t)(t + 2) * kstep; const char* b2 = last ? nB : cB + (size_t)(t + 2) * kstep;
;             const char* a3 = a2 + kstep; const char* b3 = b2 + kstep;
;             if (last && has_next) S.a_ready(nxt);
;             PG8_LDB(B0, 0, 0); PG8_SCHED; PG8_LDA(At, 0, 0); PG8_STAGE(PG8_SA(1, 1), a1 + hstepA, voffA);
;             PG8_WAIT_L(8); PG8_BAR; PG8_WAIT_L(0); PG8_MMA(0, 0, At, B0); PG8_BAR; PG8_SCHED;
;     ...
;             PG8_LDA(At, 1, 1); PG8_STAGE(PG8_SA(1, 0), a3, voffA);
;             PG8_BAR; PG8_WAIT_L(0); PG8_MMA(1, 0, At, B0); PG8_BAR; PG8_SCHED;
;             PG8_STAGE(PG8_SB(1, 1), b3 + hstepB, voffB);
;             PG8_WAIT_V(6); PG8_BAR; PG8_MMA(1, 1, At, B1); PG8_BAR;
	ds_read_b128 v[162:165], v148 offset:49152
	ds_read_b128 v[166:169], v148 offset:50176
	ds_read_b128 v[170:173], v148 offset:51200
	ds_read_b128 v[174:177], v148 offset:52224
	ds_read_b128 v[178:181], v148 offset:53248
	ds_read_b128 v[182:185], v148 offset:54272
	ds_read_b128 v[186:189], v148 offset:55296
	ds_read_b128 v[190:193], v148 offset:56320
	s_add_i32 s25, s54, s30
	v_lshl_add_u64 v[146:147], v[146:147], 0, s[8:9]
	s_mov_b32 m0, s25
	s_nop 0
	global_load_lds_dwordx4 v[146:147], off
	v_lshl_add_u64 v[146:147], v[210:211], 0, s[8:9]
	s_add_i32 m0, s25, 0x2000
	s_nop 0
	global_load_lds_dwordx4 v[146:147], off
	s_mov_b32 m0, s42
	v_lshl_add_u64 v[146:147], v[212:213], 0, s[8:9]
	global_load_lds_dwordx4 v[146:147], off
	v_lshl_add_u64 v[146:147], v[216:217], 0, s[8:9]
	s_mov_b32 m0, s43
	s_nop 0
	global_load_lds_dwordx4 v[146:147], off
	s_add_u32 s20, s20, 0x80080
	s_addc_u32 s21, s21, 0
	s_add_i32 s24, s24, s30
	s_mov_b32 m0, s24
	s_nop 0
	global_load_lds_dwordx4 v2, s[20:21]
	s_add_i32 m0, s24, 0x2000
	s_nop 0
	global_load_lds_dwordx4 v132, s[20:21]
	s_add_i32 s53, s53, 2
	s_add_u32 s18, s18, 0x100
	s_addc_u32 s19, s19, 0
	s_add_u32 s51, s51, 0x100
	s_addc_u32 s52, s52, 0
	s_cmp_gt_u32 s53, 29
	s_waitcnt lgkmcnt(0)
	s_waitcnt vmcnt(6)
	s_barrier
	v_mfma_f32_16x16x32_bf16 v[64:67], v[142:145], v[162:165], v[64:67]
	v_mfma_f32_16x16x32_bf16 v[60:63], v[154:157], v[162:165], v[60:63]
	v_mfma_f32_16x16x32_bf16 v[56:59], v[142:145], v[170:173], v[56:59]
	v_mfma_f32_16x16x32_bf16 v[48:51], v[154:157], v[170:173], v[48:51]
	v_mfma_f32_16x16x32_bf16 v[40:43], v[142:145], v[178:181], v[40:43]
	v_mfma_f32_16x16x32_bf16 v[32:35], v[154:157], v[178:181], v[32:35]
	v_mfma_f32_16x16x32_bf16 v[24:27], v[142:145], v[186:189], v[24:27]
	v_mfma_f32_16x16x32_bf16 v[16:19], v[154:157], v[186:189], v[16:19]
	v_mfma_f32_16x16x32_bf16 v[64:67], v[150:153], v[166:169], v[64:67]
	v_mfma_f32_16x16x32_bf16 v[60:63], v[158:161], v[166:169], v[60:63]
	v_mfma_f32_16x16x32_bf16 v[56:59], v[150:153], v[174:177], v[56:59]
	v_mfma_f32_16x16x32_bf16 v[48:51], v[158:161], v[174:177], v[48:51]
	v_mfma_f32_16x16x32_bf16 v[40:43], v[150:153], v[182:185], v[40:43]
	v_mfma_f32_16x16x32_bf16 v[32:35], v[158:161], v[182:185], v[32:35]
	v_mfma_f32_16x16x32_bf16 v[24:27], v[150:153], v[190:193], v[24:27]
	v_mfma_f32_16x16x32_bf16 v[16:19], v[158:161], v[190:193], v[16:19]
	v_mfma_f32_16x16x32_bf16 v[52:55], v[194:197], v[162:165], v[52:55]
	v_mfma_f32_16x16x32_bf16 v[44:47], v[202:205], v[162:165], v[44:47]
	v_mfma_f32_16x16x32_bf16 v[36:39], v[194:197], v[170:173], v[36:39]
	v_mfma_f32_16x16x32_bf16 v[28:31], v[202:205], v[170:173], v[28:31]
	v_mfma_f32_16x16x32_bf16 v[20:23], v[194:197], v[178:181], v[20:23]
	v_mfma_f32_16x16x32_bf16 v[12:15], v[202:205], v[178:181], v[12:15]
	v_mfma_f32_16x16x32_bf16 v[8:11], v[194:197], v[186:189], v[8:11]
	v_mfma_f32_16x16x32_bf16 v[4:7], v[202:205], v[186:189], v[4:7]
	v_mfma_f32_16x16x32_bf16 v[52:55], v[198:201], v[166:169], v[52:55]
	v_mfma_f32_16x16x32_bf16 v[44:47], v[206:209], v[166:169], v[44:47]
	v_mfma_f32_16x16x32_bf16 v[36:39], v[198:201], v[174:177], v[36:39]
	v_mfma_f32_16x16x32_bf16 v[28:31], v[206:209], v[174:177], v[28:31]
	v_mfma_f32_16x16x32_bf16 v[20:23], v[198:201], v[182:185], v[20:23]
	v_mfma_f32_16x16x32_bf16 v[12:15], v[206:209], v[182:185], v[12:15]
	v_mfma_f32_16x16x32_bf16 v[8:11], v[198:201], v[190:193], v[8:11]
	v_mfma_f32_16x16x32_bf16 v[4:7], v[206:209], v[190:193], v[4:7]
	s_barrier
	s_setprio 0
.LBB0_1094:
	s_add_u32 s20, s18, 0xfff80080
	s_addc_u32 s21, s19, -1
	s_add_i32 s54, 0, 0x10000
	v_add_u32_e32 v146, s54, v1
	ds_read_b128 v[142:145], v146
	ds_read_b128 v[150:153], v146 offset:1024
	ds_read_b128 v[154:157], v146 offset:2048
	ds_read_b128 v[158:161], v146 offset:3072
	s_cmp_eq_u32 s53, 28
	s_cselect_b32 s25, s5, s21
	s_cselect_b32 s24, s49, s20
	s_cselect_b32 s21, s1, s52
	s_cselect_b32 s20, s50, s51
	ds_read_b128 v[162:165], v148
	ds_read_b128 v[166:169], v148 offset:1024
	ds_read_b128 v[170:173], v148 offset:2048
	ds_read_b128 v[174:177], v148 offset:3072
	ds_read_b128 v[178:181], v148 offset:4096
	ds_read_b128 v[182:185], v148 offset:5120
	ds_read_b128 v[186:189], v148 offset:6144
	ds_read_b128 v[190:193], v148 offset:7168
	s_add_i32 s56, 0, 0x14000
	v_add_u32_e32 v146, s56, v1
	ds_read_b128 v[194:197], v146
	ds_read_b128 v[198:201], v146 offset:1024
	ds_read_b128 v[202:205], v146 offset:2048
	ds_read_b128 v[206:209], v146 offset:3072
	s_add_i32 m0, s31, 0xc000
	s_nop 0
	global_load_lds_dwordx4 v138, s[18:19]
	s_add_i32 m0, s31, 0xe000
	s_nop 0
	global_load_lds_dwordx4 v140, s[18:19]
	s_waitcnt lgkmcnt(0)
	s_barrier
; #define PG8_STAGE(bufoff, gbase, voff) do { _Pragma("unroll") for (int _i = 0; _i < 2; ++_i) \
;         __builtin_amdgcn_global_load_lds((const unsigned*)((const char*)(gbase) + (voff)[_i]), (LAS unsigned*)(lds + (bufoff) + ldsw + _i * 8192), 16, 0, 0); } while (0)
; #define PG8_LDA(dst, b, h) do { _Pragma("unroll") for (int m = 0; m < 4; ++m) _Pragma("unroll") for (int k = 0; k < 2; ++k) dst[m][k] = *(const LAS bf16x8*)(lds + PG8_SA(b, h) + aoff + m * 2048 + k * 1024); } while (0)
; #define PG8_LDB(dst, b, h) do { _Pragma("unroll") for (int n = 0; n < 2; ++n) _Pragma("unroll") for (int k = 0; k < 2; ++k) dst[n][k] = *(const LAS bf16x8*)(lds + PG8_SB(b, h) + boff + n * 2048 + k * 1024); } while (0)
; #define PG8_MMA(ai, bj, At, Bt) do { __builtin_amdgcn_s_setprio(1); _Pragma("unroll") for (int m = 0; m < 4; ++m) _Pragma("unroll") for (int n = 0; n < 2; ++n) _Pragma("unroll") for (int k = 0; k < 2; ++k) \
;         acc[ai][bj][m][n] = __builtin_amdgcn_mfma_f32_16x16x32_bf16(Bt[n][k], At[m][k], acc[ai][bj][m][n], 0, 0, 0); __builtin_amdgcn_s_setprio(0); } while (0)
; #define PG8_WAIT_V(n) asm volatile("s_waitcnt vmcnt(" #n ")" ::: "memory")
; #define PG8_WAIT_L(n) asm volatile("s_waitcnt lgkmcnt(" #n ")" ::: "memory")
; #define PG8_BAR __builtin_amdgcn_s_barrier()
; #define PG8_SCHED __builtin_amdgcn_sched_barrier(0)
; template <class Epi, class Sched>
; __device__ __forceinline__ void gemm_phase(LAS unsigned char* lds, const Gemm g, const Sched& S, const Epi& E) {
;     ...
;             PG8_WAIT_L(8); PG8_BAR; PG8_WAIT_L(0); PG8_MMA(0, 0, At, B0); PG8_BAR; PG8_SCHED;
;             PG8_LDB(B1, 0, 1); PG8_STAGE(PG8_SB(0, 0), b2, voffB);
;             PG8_BAR; PG8_WAIT_L(0); PG8_MMA(0, 1, At, B1); PG8_BAR;
;             PG8_LDA(At, 0, 1); PG8_STAGE(PG8_SA(0, 0), a2, voffA);
;             PG8_BAR; PG8_WAIT_L(0); PG8_MMA(1, 0, At, B0); PG8_BAR; PG8_SCHED;
;             PG8_STAGE(PG8_SB(0, 1), b2 + hstepB, voffB);
;             PG8_WAIT_V(6); PG8_BAR; PG8_MMA(1, 1, At, B1); PG8_BAR;
	v_mfma_f32_16x16x32_bf16 v[128:131], v[142:145], v[162:165], v[128:131]
	v_mfma_f32_16x16x32_bf16 v[124:127], v[154:157], v[162:165], v[124:127]
	v_mfma_f32_16x16x32_bf16 v[120:123], v[142:145], v[170:173], v[120:123]
	v_mfma_f32_16x16x32_bf16 v[112:115], v[154:157], v[170:173], v[112:115]
	v_mfma_f32_16x16x32_bf16 v[104:107], v[142:145], v[178:181], v[104:107]
	v_mfma_f32_16x16x32_bf16 v[96:99], v[154:157], v[178:181], v[96:99]
	v_mfma_f32_16x16x32_bf16 v[88:91], v[142:145], v[186:189], v[88:91]
	v_mfma_f32_16x16x32_bf16 v[80:83], v[154:157], v[186:189], v[80:83]
	v_mfma_f32_16x16x32_bf16 v[128:131], v[150:153], v[166:169], v[128:131]
	v_mfma_f32_16x16x32_bf16 v[124:127], v[158:161], v[166:169], v[124:127]
	v_mfma_f32_16x16x32_bf16 v[120:123], v[150:153], v[174:177], v[120:123]
	v_mfma_f32_16x16x32_bf16 v[112:115], v[158:161], v[174:177], v[112:115]
	v_mfma_f32_16x16x32_bf16 v[104:107], v[150:153], v[182:185], v[104:107]
	v_mfma_f32_16x16x32_bf16 v[96:99], v[158:161], v[182:185], v[96:99]
	v_mfma_f32_16x16x32_bf16 v[88:91], v[150:153], v[190:193], v[88:91]
	v_mfma_f32_16x16x32_bf16 v[80:83], v[158:161], v[190:193], v[80:83]
	v_mfma_f32_16x16x32_bf16 v[116:119], v[194:197], v[162:165], v[116:119]
	v_mfma_f32_16x16x32_bf16 v[108:111], v[202:205], v[162:165], v[108:111]
	v_mfma_f32_16x16x32_bf16 v[100:103], v[194:197], v[170:173], v[100:103]
	v_mfma_f32_16x16x32_bf16 v[92:95], v[202:205], v[170:173], v[92:95]
	v_mfma_f32_16x16x32_bf16 v[84:87], v[194:197], v[178:181], v[84:87]
	v_mfma_f32_16x16x32_bf16 v[76:79], v[202:205], v[178:181], v[76:79]
	v_mfma_f32_16x16x32_bf16 v[72:75], v[194:197], v[186:189], v[72:75]
	v_mfma_f32_16x16x32_bf16 v[68:71], v[202:205], v[186:189], v[68:71]
	v_mfma_f32_16x16x32_bf16 v[116:119], v[198:201], v[166:169], v[116:119]
	v_mfma_f32_16x16x32_bf16 v[108:111], v[206:209], v[166:169], v[108:111]
	v_mfma_f32_16x16x32_bf16 v[100:103], v[198:201], v[174:177], v[100:103]
	v_mfma_f32_16x16x32_bf16 v[92:95], v[206:209], v[174:177], v[92:95]
	v_mfma_f32_16x16x32_bf16 v[84:87], v[198:201], v[182:185], v[84:87]
	v_mfma_f32_16x16x32_bf16 v[76:79], v[206:209], v[182:185], v[76:79]
	v_mfma_f32_16x16x32_bf16 v[72:75], v[198:201], v[190:193], v[72:75]
	v_mfma_f32_16x16x32_bf16 v[68:71], v[206:209], v[190:193], v[68:71]
	s_barrier
	ds_read_b128 v[162:165], v148 offset:16384
	ds_read_b128 v[166:169], v148 offset:17408
	ds_read_b128 v[170:173], v148 offset:18432
	ds_read_b128 v[174:177], v148 offset:19456
	ds_read_b128 v[178:181], v148 offset:20480
	ds_read_b128 v[182:185], v148 offset:21504
	ds_read_b128 v[186:189], v148 offset:22528
	ds_read_b128 v[190:193], v148 offset:23552
	s_add_i32 s54, s54, s30
	v_lshl_add_u64 v[146:147], s[20:21], 0, v[2:3]
	s_mov_b32 m0, s54
	v_lshl_add_u64 v[210:211], s[20:21], 0, v[132:133]
	global_load_lds_dwordx4 v[146:147], off
	s_add_i32 m0, s54, 0x2000
	s_nop 0
	global_load_lds_dwordx4 v[210:211], off
	s_mov_b32 m0, s31
	v_lshl_add_u64 v[212:213], s[24:25], 0, v[136:137]
	global_load_lds_dwordx4 v[212:213], off
	v_lshl_add_u64 v[216:217], s[24:25], 0, v[134:135]
	s_mov_b32 m0, s35
	s_nop 0
	global_load_lds_dwordx4 v[216:217], off
	s_add_u32 s54, s20, 0x80000
	s_addc_u32 s55, s21, 0
	s_add_i32 s56, s56, s30
	s_mov_b32 m0, s56
	s_nop 0
	global_load_lds_dwordx4 v2, s[54:55]
	s_add_i32 m0, s56, 0x2000
	s_nop 0
	global_load_lds_dwordx4 v132, s[54:55]
	s_nop 0
	s_waitcnt lgkmcnt(0)
	s_waitcnt vmcnt(6)
	s_barrier
	v_mfma_f32_16x16x32_bf16 v[64:67], v[142:145], v[162:165], v[64:67]
	v_mfma_f32_16x16x32_bf16 v[60:63], v[154:157], v[162:165], v[60:63]
	v_mfma_f32_16x16x32_bf16 v[56:59], v[142:145], v[170:173], v[56:59]
	v_mfma_f32_16x16x32_bf16 v[48:51], v[154:157], v[170:173], v[48:51]
	v_mfma_f32_16x16x32_bf16 v[40:43], v[142:145], v[178:181], v[40:43]
	v_mfma_f32_16x16x32_bf16 v[32:35], v[154:157], v[178:181], v[32:35]
	v_mfma_f32_16x16x32_bf16 v[24:27], v[142:145], v[186:189], v[24:27]
	v_mfma_f32_16x16x32_bf16 v[16:19], v[154:157], v[186:189], v[16:19]
	v_mfma_f32_16x16x32_bf16 v[64:67], v[150:153], v[166:169], v[64:67]
	v_mfma_f32_16x16x32_bf16 v[60:63], v[158:161], v[166:169], v[60:63]
	v_mfma_f32_16x16x32_bf16 v[56:59], v[150:153], v[174:177], v[56:59]
	v_mfma_f32_16x16x32_bf16 v[48:51], v[158:161], v[174:177], v[48:51]
	v_mfma_f32_16x16x32_bf16 v[40:43], v[150:153], v[182:185], v[40:43]
	v_mfma_f32_16x16x32_bf16 v[32:35], v[158:161], v[182:185], v[32:35]
	v_mfma_f32_16x16x32_bf16 v[24:27], v[150:153], v[190:193], v[24:27]
	v_mfma_f32_16x16x32_bf16 v[16:19], v[158:161], v[190:193], v[16:19]
	v_mfma_f32_16x16x32_bf16 v[52:55], v[194:197], v[162:165], v[52:55]
	v_mfma_f32_16x16x32_bf16 v[44:47], v[202:205], v[162:165], v[44:47]
	v_mfma_f32_16x16x32_bf16 v[36:39], v[194:197], v[170:173], v[36:39]
	v_mfma_f32_16x16x32_bf16 v[28:31], v[202:205], v[170:173], v[28:31]
	v_mfma_f32_16x16x32_bf16 v[20:23], v[194:197], v[178:181], v[20:23]
	v_mfma_f32_16x16x32_bf16 v[12:15], v[202:205], v[178:181], v[12:15]
	v_mfma_f32_16x16x32_bf16 v[8:11], v[194:197], v[186:189], v[8:11]
	v_mfma_f32_16x16x32_bf16 v[4:7], v[202:205], v[186:189], v[4:7]
	v_mfma_f32_16x16x32_bf16 v[52:55], v[198:201], v[166:169], v[52:55]
	v_mfma_f32_16x16x32_bf16 v[44:47], v[206:209], v[166:169], v[44:47]
	v_mfma_f32_16x16x32_bf16 v[36:39], v[198:201], v[174:177], v[36:39]
	v_mfma_f32_16x16x32_bf16 v[28:31], v[206:209], v[174:177], v[28:31]
	v_mfma_f32_16x16x32_bf16 v[20:23], v[198:201], v[182:185], v[20:23]
	v_mfma_f32_16x16x32_bf16 v[12:15], v[206:209], v[182:185], v[12:15]
	v_mfma_f32_16x16x32_bf16 v[8:11], v[198:201], v[190:193], v[8:11]
	v_mfma_f32_16x16x32_bf16 v[4:7], v[206:209], v[190:193], v[4:7]
	s_barrier
; #define PG8_STAGE(bufoff, gbase, voff) do { _Pragma("unroll") for (int _i = 0; _i < 2; ++_i) \
;         __builtin_amdgcn_global_load_lds((const unsigned*)((const char*)(gbase) + (voff)[_i]), (LAS unsigned*)(lds + (bufoff) + ldsw + _i * 8192), 16, 0, 0); } while (0)
; #define PG8_LDA(dst, b, h) do { _Pragma("unroll") for (int m = 0; m < 4; ++m) _Pragma("unroll") for (int k = 0; k < 2; ++k) dst[m][k] = *(const LAS bf16x8*)(lds + PG8_SA(b, h) + aoff + m * 2048 + k * 1024); } while (0)
; #define PG8_LDB(dst, b, h) do { _Pragma("unroll") for (int n = 0; n < 2; ++n) _Pragma("unroll") for (int k = 0; k < 2; ++k) dst[n][k] = *(const LAS bf16x8*)(lds + PG8_SB(b, h) + boff + n * 2048 + k * 1024); } while (0)
; #define PG8_MMA(ai, bj, At, Bt) do { __builtin_amdgcn_s_setprio(1); _Pragma("unroll") for (int m = 0; m < 4; ++m) _Pragma("unroll") for (int n = 0; n < 2; ++n) _Pragma("unroll") for (int k = 0; k < 2; ++k) \
;         acc[ai][bj][m][n] = __builtin_amdgcn_mfma_f32_16x16x32_bf16(Bt[n][k], At[m][k], acc[ai][bj][m][n], 0, 0, 0); __builtin_amdgcn_s_setprio(0); } while (0)
; #define PG8_WAIT_V(n) asm volatile("s_waitcnt vmcnt(" #n ")" ::: "memory")
; #define PG8_WAIT_L(n) asm volatile("s_waitcnt lgkmcnt(" #n ")" ::: "memory")
; #define PG8_BAR __builtin_amdgcn_s_barrier()
; #define PG8_SCHED __builtin_amdgcn_sched_barrier(0)
; template <class Epi, class Sched>
; __device__ __forceinline__ void gemm_phase(LAS unsigned char* lds, const Gemm g, const Sched& S, const Epi& E) {
;     ...
;             PG8_LDB(B0, 1, 0); PG8_SCHED; PG8_LDA(At, 1, 0); PG8_STAGE(PG8_SA(0, 1), a2 + hstepA, voffA);
;             PG8_WAIT_L(8); PG8_BAR; PG8_WAIT_L(0); PG8_MMA(0, 0, At, B0); PG8_BAR; PG8_SCHED;
;             PG8_LDB(B1, 1, 1); PG8_STAGE(PG8_SB(1, 0), b3, voffB);
;             PG8_BAR; PG8_WAIT_L(0); PG8_MMA(0, 1, At, B1); PG8_BAR;
;             PG8_LDA(At, 1, 1); PG8_STAGE(PG8_SA(1, 0), a3, voffA);
;             PG8_BAR; PG8_WAIT_L(0); PG8_MMA(1, 0, At, B0); PG8_BAR; PG8_SCHED;
;             PG8_STAGE(PG8_SB(1, 1), b3 + hstepB, voffB);
;             PG8_WAIT_V(6); PG8_BAR; PG8_MMA(1, 1, At, B1); PG8_BAR;
;         }
	s_add_i32 s54, 0, 0x18000
	v_add_u32_e32 v149, s54, v1
	ds_read_b128 v[142:145], v149
	ds_read_b128 v[150:153], v149 offset:1024
	ds_read_b128 v[154:157], v149 offset:2048
	ds_read_b128 v[158:161], v149 offset:3072
	s_add_u32 s24, s24, 0x80000
	s_addc_u32 s25, s25, 0
	ds_read_b128 v[162:165], v148 offset:32768
	ds_read_b128 v[166:169], v148 offset:33792
	ds_read_b128 v[170:173], v148 offset:34816
	ds_read_b128 v[174:177], v148 offset:35840
	ds_read_b128 v[178:181], v148 offset:36864
	ds_read_b128 v[182:185], v148 offset:37888
	ds_read_b128 v[186:189], v148 offset:38912
	ds_read_b128 v[190:193], v148 offset:39936
	s_mov_b32 m0, s36
	s_nop 0
	global_load_lds_dwordx4 v136, s[24:25]
	s_mov_b32 m0, s37
	s_nop 0
	global_load_lds_dwordx4 v134, s[24:25]
	s_add_i32 s24, 0, 0x1c000
	v_add_u32_e32 v149, s24, v1
	ds_read_b128 v[194:197], v149
	ds_read_b128 v[198:201], v149 offset:1024
	ds_read_b128 v[202:205], v149 offset:2048
	ds_read_b128 v[206:209], v149 offset:3072
	s_waitcnt lgkmcnt(0)
	s_barrier
	v_mfma_f32_16x16x32_bf16 v[128:131], v[142:145], v[162:165], v[128:131]
	v_mfma_f32_16x16x32_bf16 v[124:127], v[154:157], v[162:165], v[124:127]
	v_mfma_f32_16x16x32_bf16 v[120:123], v[142:145], v[170:173], v[120:123]
	v_mfma_f32_16x16x32_bf16 v[112:115], v[154:157], v[170:173], v[112:115]
	v_mfma_f32_16x16x32_bf16 v[104:107], v[142:145], v[178:181], v[104:107]
	v_mfma_f32_16x16x32_bf16 v[96:99], v[154:157], v[178:181], v[96:99]
	v_mfma_f32_16x16x32_bf16 v[88:91], v[142:145], v[186:189], v[88:91]
	v_mfma_f32_16x16x32_bf16 v[80:83], v[154:157], v[186:189], v[80:83]
	v_mfma_f32_16x16x32_bf16 v[128:131], v[150:153], v[166:169], v[128:131]
	v_mfma_f32_16x16x32_bf16 v[124:127], v[158:161], v[166:169], v[124:127]
	v_mfma_f32_16x16x32_bf16 v[120:123], v[150:153], v[174:177], v[120:123]
	v_mfma_f32_16x16x32_bf16 v[112:115], v[158:161], v[174:177], v[112:115]
	v_mfma_f32_16x16x32_bf16 v[104:107], v[150:153], v[182:185], v[104:107]
	v_mfma_f32_16x16x32_bf16 v[96:99], v[158:161], v[182:185], v[96:99]
	v_mfma_f32_16x16x32_bf16 v[88:91], v[150:153], v[190:193], v[88:91]
	v_mfma_f32_16x16x32_bf16 v[80:83], v[158:161], v[190:193], v[80:83]
	v_mfma_f32_16x16x32_bf16 v[116:119], v[194:197], v[162:165], v[116:119]
	v_mfma_f32_16x16x32_bf16 v[108:111], v[202:205], v[162:165], v[108:111]
	v_mfma_f32_16x16x32_bf16 v[100:103], v[194:197], v[170:173], v[100:103]
	v_mfma_f32_16x16x32_bf16 v[92:95], v[202:205], v[170:173], v[92:95]
	v_mfma_f32_16x16x32_bf16 v[84:87], v[194:197], v[178:181], v[84:87]
	v_mfma_f32_16x16x32_bf16 v[76:79], v[202:205], v[178:181], v[76:79]
	v_mfma_f32_16x16x32_bf16 v[72:75], v[194:197], v[186:189], v[72:75]
	v_mfma_f32_16x16x32_bf16 v[68:71], v[202:205], v[186:189], v[68:71]
	v_mfma_f32_16x16x32_bf16 v[116:119], v[198:201], v[166:169], v[116:119]
	v_mfma_f32_16x16x32_bf16 v[108:111], v[206:209], v[166:169], v[108:111]
	v_mfma_f32_16x16x32_bf16 v[100:103], v[198:201], v[174:177], v[100:103]
	v_mfma_f32_16x16x32_bf16 v[92:95], v[206:209], v[174:177], v[92:95]
	v_mfma_f32_16x16x32_bf16 v[84:87], v[198:201], v[182:185], v[84:87]
	v_mfma_f32_16x16x32_bf16 v[76:79], v[206:209], v[182:185], v[76:79]
	v_mfma_f32_16x16x32_bf16 v[72:75], v[198:201], v[190:193], v[72:75]
	v_mfma_f32_16x16x32_bf16 v[68:71], v[206:209], v[190:193], v[68:71]
	s_barrier
	ds_read_b128 v[162:165], v148 offset:49152
	ds_read_b128 v[166:169], v148 offset:50176
	ds_read_b128 v[170:173], v148 offset:51200
	ds_read_b128 v[174:177], v148 offset:52224
	ds_read_b128 v[178:181], v148 offset:53248
	ds_read_b128 v[182:185], v148 offset:54272
	ds_read_b128 v[186:189], v148 offset:55296
	ds_read_b128 v[190:193], v148 offset:56320
	s_add_i32 s25, s54, s30
	v_lshl_add_u64 v[146:147], v[146:147], 0, s[8:9]
	s_mov_b32 m0, s25
	s_nop 0
	global_load_lds_dwordx4 v[146:147], off
	v_lshl_add_u64 v[146:147], v[210:211], 0, s[8:9]
	s_add_i32 m0, s25, 0x2000
	s_nop 0
	global_load_lds_dwordx4 v[146:147], off
	s_mov_b32 m0, s42
	v_lshl_add_u64 v[146:147], v[212:213], 0, s[8:9]
	global_load_lds_dwordx4 v[146:147], off
	v_lshl_add_u64 v[146:147], v[216:217], 0, s[8:9]
	s_mov_b32 m0, s43
	s_nop 0
	global_load_lds_dwordx4 v[146:147], off
	s_add_u32 s20, s20, 0x80080
	s_addc_u32 s21, s21, 0
	s_add_i32 s24, s24, s30
	s_mov_b32 m0, s24
	s_nop 0
	global_load_lds_dwordx4 v2, s[20:21]
	s_add_i32 m0, s24, 0x2000
	s_nop 0
	global_load_lds_dwordx4 v132, s[20:21]
	s_add_i32 s53, s53, 2
	s_add_u32 s18, s18, 0x100
	s_addc_u32 s19, s19, 0
	s_add_u32 s51, s51, 0x100
	s_addc_u32 s52, s52, 0
	s_cmp_gt_u32 s53, 29
	s_waitcnt lgkmcnt(0)
	s_waitcnt vmcnt(6)
	s_barrier
	v_mfma_f32_16x16x32_bf16 v[64:67], v[142:145], v[162:165], v[64:67]
	v_mfma_f32_16x16x32_bf16 v[60:63], v[154:157], v[162:165], v[60:63]
	v_mfma_f32_16x16x32_bf16 v[56:59], v[142:145], v[170:173], v[56:59]
	v_mfma_f32_16x16x32_bf16 v[48:51], v[154:157], v[170:173], v[48:51]
	v_mfma_f32_16x16x32_bf16 v[40:43], v[142:145], v[178:181], v[40:43]
	v_mfma_f32_16x16x32_bf16 v[32:35], v[154:157], v[178:181], v[32:35]
	v_mfma_f32_16x16x32_bf16 v[24:27], v[142:145], v[186:189], v[24:27]
	v_mfma_f32_16x16x32_bf16 v[16:19], v[154:157], v[186:189], v[16:19]
	v_mfma_f32_16x16x32_bf16 v[64:67], v[150:153], v[166:169], v[64:67]
	v_mfma_f32_16x16x32_bf16 v[60:63], v[158:161], v[166:169], v[60:63]
	v_mfma_f32_16x16x32_bf16 v[56:59], v[150:153], v[174:177], v[56:59]
	v_mfma_f32_16x16x32_bf16 v[48:51], v[158:161], v[174:177], v[48:51]
	v_mfma_f32_16x16x32_bf16 v[40:43], v[150:153], v[182:185], v[40:43]
	v_mfma_f32_16x16x32_bf16 v[32:35], v[158:161], v[182:185], v[32:35]
	v_mfma_f32_16x16x32_bf16 v[24:27], v[150:153], v[190:193], v[24:27]
	v_mfma_f32_16x16x32_bf16 v[16:19], v[158:161], v[190:193], v[16:19]
	v_mfma_f32_16x16x32_bf16 v[52:55], v[194:197], v[162:165], v[52:55]
	v_mfma_f32_16x16x32_bf16 v[44:47], v[202:205], v[162:165], v[44:47]
	v_mfma_f32_16x16x32_bf16 v[36:39], v[194:197], v[170:173], v[36:39]
	v_mfma_f32_16x16x32_bf16 v[28:31], v[202:205], v[170:173], v[28:31]
	v_mfma_f32_16x16x32_bf16 v[20:23], v[194:197], v[178:181], v[20:23]
	v_mfma_f32_16x16x32_bf16 v[12:15], v[202:205], v[178:181], v[12:15]
	v_mfma_f32_16x16x32_bf16 v[8:11], v[194:197], v[186:189], v[8:11]
	v_mfma_f32_16x16x32_bf16 v[4:7], v[202:205], v[186:189], v[4:7]
	v_mfma_f32_16x16x32_bf16 v[52:55], v[198:201], v[166:169], v[52:55]
	v_mfma_f32_16x16x32_bf16 v[44:47], v[206:209], v[166:169], v[44:47]
	v_mfma_f32_16x16x32_bf16 v[36:39], v[198:201], v[174:177], v[36:39]
	v_mfma_f32_16x16x32_bf16 v[28:31], v[206:209], v[174:177], v[28:31]
	v_mfma_f32_16x16x32_bf16 v[20:23], v[198:201], v[182:185], v[20:23]
	v_mfma_f32_16x16x32_bf16 v[12:15], v[206:209], v[182:185], v[12:15]
	v_mfma_f32_16x16x32_bf16 v[8:11], v[198:201], v[190:193], v[8:11]
	v_mfma_f32_16x16x32_bf16 v[4:7], v[206:209], v[190:193], v[4:7]
	s_barrier
	s_cbranch_scc0 .LBB0_1094
	s_cmpk_gt_u32 s2, 0xff
	s_cbranch_scc1 .Lalign_a_1094
	s_barrier

;     __device__ __forceinline__ void prefetch(const Unit& u, int ui) const { if (rs) rs_prefetch(rs, u.pm, ui); }
;     __device__ __forceinline__ void prefetch(const Unit& u, int ui) const { rs_prefetch(rs, u.pm, ui); }
; #define PG8_STAGE(bufoff, gbase, voff) do { _Pragma("unroll") for (int _i = 0; _i < 2; ++_i) \
;         __builtin_amdgcn_global_load_lds((const unsigned*)((const char*)(gbase) + (voff)[_i]), (LAS unsigned*)(lds + (bufoff) + ldsw + _i * 8192), 16, 0, 0); } while (0)
; #define PG8_LDA(dst, b, h) do { _Pragma("unroll") for (int m = 0; m < 4; ++m) _Pragma("unroll") for (int k = 0; k < 2; ++k) dst[m][k] = *(const LAS bf16x8*)(lds + PG8_SA(b, h) + aoff + m * 2048 + k * 1024); } while (0)
; #define PG8_LDB(dst, b, h) do { _Pragma("unroll") for (int n = 0; n < 2; ++n) _Pragma("unroll") for (int k = 0; k < 2; ++k) dst[n][k] = *(const LAS bf16x8*)(lds + PG8_SB(b, h) + boff + n * 2048 + k * 1024); } while (0)
; template <class Epi, class Sched>
; __device__ __forceinline__ void gemm_phase(LAS unsigned char* lds, const Gemm g, const Sched& S, const Epi& E) {
;     ...
;     for (;;) {
;         E.prefetch(cur, ui);
;         const bool has_next = S.next(ui + 1, nxt);
;         const char* nA = has_next ? (const char*)g.A + (size_t)nxt.pm * tstepA : cA; const char* nB = has_next ? (const char*)g.Bt + (size_t)nxt.pn * tstepB : cB;
;         for (int t = 0; t < nt; t += 2) {
;             const bool last = (t == nt - 2);
;             const char* a1 = cA + (size_t)(t + 1) * kstep;
;             const char* a2 = last ? nA : cA + (size_t)(t + 2) * kstep; const char* b2 = last ? nB : cB + (size_t)(t + 2) * kstep;
;             const char* a3 = a2 + kstep; const char* b3 = b2 + kstep;
;             if (last && has_next) S.a_ready(nxt);
;             PG8_LDB(B0, 0, 0); PG8_SCHED; PG8_LDA(At, 0, 0); PG8_STAGE(PG8_SA(1, 1), a1 + hstepA, voffA);
;             PG8_WAIT_L(8); PG8_BAR; PG8_WAIT_L(0); PG8_MMA(0, 0, At, B0); PG8_BAR; PG8_SCHED;
;             PG8_LDB(B1, 0, 1); PG8_STAGE(PG8_SB(0, 0), b2, voffB);
;             PG8_BAR; PG8_WAIT_L(0); PG8_MMA(0, 1, At, B1); PG8_BAR;
;             PG8_LDA(At, 0, 1); PG8_STAGE(PG8_SA(0, 0), a2, voffA);
;             PG8_BAR; PG8_WAIT_L(0); PG8_MMA(1, 0, At, B0); PG8_BAR; PG8_SCHED;
;             PG8_STAGE(PG8_SB(0, 1), b2 + hstepB, voffB);
;             PG8_WAIT_V(6); PG8_BAR; PG8_MMA(1, 1, At, B1); PG8_BAR;
.LBB0_1395:
	v_mov_b64_e32 v[4:5], 0x400
	s_ashr_i32 s15, s14, 31
	v_cmp_lt_i64_e32 vcc, s[4:5], v[4:5]
	s_lshl_b64 s[4:5], s[14:15], 20
	v_readlane_b32 s48, v252, 0
	v_readlane_b32 s49, v252, 1
	s_add_u32 s4, s48, s4
	s_addc_u32 s5, s49, s5
	s_and_b64 s[18:19], vcc, exec
	s_cselect_b32 s15, s5, s7
	s_cselect_b32 s47, s4, s6
	s_ashr_i32 s1, s0, 31
	s_lshl_b64 s[18:19], s[0:1], 20
	s_add_u32 s18, s28, s18
	s_addc_u32 s19, s29, s19
	s_and_b64 s[24:25], vcc, exec
	s_cselect_b32 s1, s19, s21
	s_cselect_b32 s48, s18, s20
	s_add_u32 s6, s6, 0x80080
	s_addc_u32 s7, s7, 0
	v_readlane_b32 s50, v252, 2
	v_readlane_b32 s51, v252, 3
	s_add_u32 s49, s20, 0x100
	s_addc_u32 s50, s21, 0
	s_mov_b32 s51, -2
	s_add_u32 s20, s6, 0xfff80080
	s_addc_u32 s21, s7, -1
	s_add_i32 s52, 0, 0x10000
	v_add_u32_e32 v144, s52, v1
	ds_read_b128 v[132:135], v144
	ds_read_b128 v[136:139], v144 offset:1024
	ds_read_b128 v[140:143], v144 offset:2048
	ds_read_b128 v[144:147], v144 offset:3072
	s_cmp_eq_u32 s51, 28
	s_cselect_b32 s25, s15, s21
	s_cselect_b32 s24, s47, s20
	s_cselect_b32 s21, s1, s50
	s_cselect_b32 s20, s48, s49
	ds_read_b128 v[148:151], v224
	ds_read_b128 v[152:155], v224 offset:1024
	ds_read_b128 v[156:159], v224 offset:2048
	ds_read_b128 v[160:163], v224 offset:3072
	ds_read_b128 v[164:167], v224 offset:4096
	ds_read_b128 v[168:171], v224 offset:5120
	ds_read_b128 v[172:175], v224 offset:6144
	ds_read_b128 v[176:179], v224 offset:7168
	s_add_i32 s54, 0, 0x14000
	v_add_u32_e32 v202, s54, v1
	ds_read_b128 v[180:183], v202
	ds_read_b128 v[184:187], v202 offset:1024
	ds_read_b128 v[188:191], v202 offset:2048
	ds_read_b128 v[202:205], v202 offset:3072
	s_add_i32 m0, s31, 0xc000
	s_nop 0
	global_load_lds_dwordx4 v198, s[6:7]
	s_add_i32 m0, s31, 0xe000
	s_nop 0
	global_load_lds_dwordx4 v200, s[6:7]
	s_nop 0
	s_waitcnt lgkmcnt(0)
	s_barrier
	v_mfma_f32_16x16x32_bf16 v[128:131], v[132:135], v[148:151], 0
	v_mfma_f32_16x16x32_bf16 v[124:127], v[140:143], v[148:151], 0
	v_mfma_f32_16x16x32_bf16 v[112:115], v[132:135], v[156:159], 0
	v_mfma_f32_16x16x32_bf16 v[108:111], v[140:143], v[156:159], 0
	v_mfma_f32_16x16x32_bf16 v[100:103], v[132:135], v[164:167], 0
	v_mfma_f32_16x16x32_bf16 v[92:95], v[140:143], v[164:167], 0
	v_mfma_f32_16x16x32_bf16 v[84:87], v[132:135], v[172:175], 0
	v_mfma_f32_16x16x32_bf16 v[76:79], v[140:143], v[172:175], 0
	v_mfma_f32_16x16x32_bf16 v[128:131], v[136:139], v[152:155], v[128:131]
	v_mfma_f32_16x16x32_bf16 v[124:127], v[144:147], v[152:155], v[124:127]
	v_mfma_f32_16x16x32_bf16 v[112:115], v[136:139], v[160:163], v[112:115]
	v_mfma_f32_16x16x32_bf16 v[108:111], v[144:147], v[160:163], v[108:111]
	v_mfma_f32_16x16x32_bf16 v[100:103], v[136:139], v[168:171], v[100:103]
	v_mfma_f32_16x16x32_bf16 v[92:95], v[144:147], v[168:171], v[92:95]
	v_mfma_f32_16x16x32_bf16 v[84:87], v[136:139], v[176:179], v[84:87]
	v_mfma_f32_16x16x32_bf16 v[76:79], v[144:147], v[176:179], v[76:79]
	v_mfma_f32_16x16x32_bf16 v[120:123], v[180:183], v[148:151], 0
	v_mfma_f32_16x16x32_bf16 v[116:119], v[188:191], v[148:151], 0
	v_mfma_f32_16x16x32_bf16 v[104:107], v[180:183], v[156:159], 0
	v_mfma_f32_16x16x32_bf16 v[96:99], v[188:191], v[156:159], 0
	v_mfma_f32_16x16x32_bf16 v[88:91], v[180:183], v[164:167], 0
	v_mfma_f32_16x16x32_bf16 v[80:83], v[188:191], v[164:167], 0
	v_mfma_f32_16x16x32_bf16 v[72:75], v[180:183], v[172:175], 0
	v_mfma_f32_16x16x32_bf16 v[68:71], v[188:191], v[172:175], 0
	v_mfma_f32_16x16x32_bf16 v[120:123], v[184:187], v[152:155], v[120:123]
	v_mfma_f32_16x16x32_bf16 v[116:119], v[202:205], v[152:155], v[116:119]
	v_mfma_f32_16x16x32_bf16 v[104:107], v[184:187], v[160:163], v[104:107]
	v_mfma_f32_16x16x32_bf16 v[96:99], v[202:205], v[160:163], v[96:99]
	v_mfma_f32_16x16x32_bf16 v[88:91], v[184:187], v[168:171], v[88:91]
	v_mfma_f32_16x16x32_bf16 v[80:83], v[202:205], v[168:171], v[80:83]
	v_mfma_f32_16x16x32_bf16 v[72:75], v[184:187], v[176:179], v[72:75]
	v_mfma_f32_16x16x32_bf16 v[68:71], v[202:205], v[176:179], v[68:71]
	s_barrier
	ds_read_b128 v[148:151], v224 offset:16384
	ds_read_b128 v[152:155], v224 offset:17408
	ds_read_b128 v[156:159], v224 offset:18432
	ds_read_b128 v[160:163], v224 offset:19456
	ds_read_b128 v[164:167], v224 offset:20480
	ds_read_b128 v[168:171], v224 offset:21504
	ds_read_b128 v[172:175], v224 offset:22528
	ds_read_b128 v[176:179], v224 offset:23552
	s_add_i32 s52, s52, s30
	v_lshl_add_u64 v[206:207], s[20:21], 0, v[2:3]
	s_mov_b32 m0, s52
	s_nop 0
	global_load_lds_dwordx4 v[206:207], off
	v_lshl_add_u64 v[208:209], s[20:21], 0, v[192:193]
	s_add_i32 m0, s52, 0x2000
	s_nop 0
	global_load_lds_dwordx4 v[208:209], off
	s_mov_b32 m0, s31
	v_lshl_add_u64 v[210:211], s[24:25], 0, v[196:197]
	global_load_lds_dwordx4 v[210:211], off
	v_lshl_add_u64 v[212:213], s[24:25], 0, v[194:195]
	s_mov_b32 m0, s35
	s_nop 0
	global_load_lds_dwordx4 v[212:213], off
	s_add_u32 s52, s20, 0x80000
	s_addc_u32 s53, s21, 0
	s_add_i32 s54, s54, s30
	s_mov_b32 m0, s54
	s_nop 0
	global_load_lds_dwordx4 v2, s[52:53]
	s_add_i32 m0, s54, 0x2000
	s_nop 0
	global_load_lds_dwordx4 v192, s[52:53]
	s_waitcnt lgkmcnt(0)
	s_waitcnt vmcnt(6)
	s_barrier
; #define PG8_STAGE(bufoff, gbase, voff) do { _Pragma("unroll") for (int _i = 0; _i < 2; ++_i) \
;         __builtin_amdgcn_global_load_lds((const unsigned*)((const char*)(gbase) + (voff)[_i]), (LAS unsigned*)(lds + (bufoff) + ldsw + _i * 8192), 16, 0, 0); } while (0)
; #define PG8_LDA(dst, b, h) do { _Pragma("unroll") for (int m = 0; m < 4; ++m) _Pragma("unroll") for (int k = 0; k < 2; ++k) dst[m][k] = *(const LAS bf16x8*)(lds + PG8_SA(b, h) + aoff + m * 2048 + k * 1024); } while (0)
; #define PG8_LDB(dst, b, h) do { _Pragma("unroll") for (int n = 0; n < 2; ++n) _Pragma("unroll") for (int k = 0; k < 2; ++k) dst[n][k] = *(const LAS bf16x8*)(lds + PG8_SB(b, h) + boff + n * 2048 + k * 1024); } while (0)
; #define PG8_MMA(ai, bj, At, Bt) do { __builtin_amdgcn_s_setprio(1); _Pragma("unroll") for (int m = 0; m < 4; ++m) _Pragma("unroll") for (int n = 0; n < 2; ++n) _Pragma("unroll") for (int k = 0; k < 2; ++k) \
;         acc[ai][bj][m][n] = __builtin_amdgcn_mfma_f32_16x16x32_bf16(Bt[n][k], At[m][k], acc[ai][bj][m][n], 0, 0, 0); __builtin_amdgcn_s_setprio(0); } while (0)
; #define PG8_WAIT_V(n) asm volatile("s_waitcnt vmcnt(" #n ")" ::: "memory")
; #define PG8_WAIT_L(n) asm volatile("s_waitcnt lgkmcnt(" #n ")" ::: "memory")
; #define PG8_BAR __builtin_amdgcn_s_barrier()
; #define PG8_SCHED __builtin_amdgcn_sched_barrier(0)
; template <class Epi, class Sched>
; __device__ __forceinline__ void gemm_phase(LAS unsigned char* lds, const Gemm g, const Sched& S, const Epi& E) {
;     ...
;             PG8_BAR; PG8_WAIT_L(0); PG8_MMA(1, 0, At, B0); PG8_BAR; PG8_SCHED;
;             PG8_STAGE(PG8_SB(0, 1), b2 + hstepB, voffB);
;             PG8_WAIT_V(6); PG8_BAR; PG8_MMA(1, 1, At, B1); PG8_BAR;
;             PG8_LDB(B0, 1, 0); PG8_SCHED; PG8_LDA(At, 1, 0); PG8_STAGE(PG8_SA(0, 1), a2 + hstepA, voffA);
;             PG8_WAIT_L(8); PG8_BAR; PG8_WAIT_L(0); PG8_MMA(0, 0, At, B0); PG8_BAR; PG8_SCHED;
;             PG8_LDB(B1, 1, 1); PG8_STAGE(PG8_SB(1, 0), b3, voffB);
;             PG8_BAR; PG8_WAIT_L(0); PG8_MMA(0, 1, At, B1); PG8_BAR;
	v_mfma_f32_16x16x32_bf16 v[64:67], v[132:135], v[148:151], 0
	v_mfma_f32_16x16x32_bf16 v[60:63], v[140:143], v[148:151], 0
	v_mfma_f32_16x16x32_bf16 v[52:55], v[132:135], v[156:159], 0
	v_mfma_f32_16x16x32_bf16 v[44:47], v[140:143], v[156:159], 0
	v_mfma_f32_16x16x32_bf16 v[36:39], v[132:135], v[164:167], 0
	v_mfma_f32_16x16x32_bf16 v[28:31], v[140:143], v[164:167], 0
	v_mfma_f32_16x16x32_bf16 v[20:23], v[132:135], v[172:175], 0
	v_mfma_f32_16x16x32_bf16 v[12:15], v[140:143], v[172:175], 0
	v_mfma_f32_16x16x32_bf16 v[64:67], v[136:139], v[152:155], v[64:67]
	v_mfma_f32_16x16x32_bf16 v[60:63], v[144:147], v[152:155], v[60:63]
	v_mfma_f32_16x16x32_bf16 v[52:55], v[136:139], v[160:163], v[52:55]
	v_mfma_f32_16x16x32_bf16 v[44:47], v[144:147], v[160:163], v[44:47]
	v_mfma_f32_16x16x32_bf16 v[36:39], v[136:139], v[168:171], v[36:39]
	v_mfma_f32_16x16x32_bf16 v[28:31], v[144:147], v[168:171], v[28:31]
	v_mfma_f32_16x16x32_bf16 v[20:23], v[136:139], v[176:179], v[20:23]
	v_mfma_f32_16x16x32_bf16 v[12:15], v[144:147], v[176:179], v[12:15]
	v_mfma_f32_16x16x32_bf16 v[56:59], v[180:183], v[148:151], 0
	v_mfma_f32_16x16x32_bf16 v[48:51], v[188:191], v[148:151], 0
	v_mfma_f32_16x16x32_bf16 v[40:43], v[180:183], v[156:159], 0
	v_mfma_f32_16x16x32_bf16 v[32:35], v[188:191], v[156:159], 0
	v_mfma_f32_16x16x32_bf16 v[24:27], v[180:183], v[164:167], 0
	v_mfma_f32_16x16x32_bf16 v[16:19], v[188:191], v[164:167], 0
	v_mfma_f32_16x16x32_bf16 v[8:11], v[180:183], v[172:175], 0
	v_mfma_f32_16x16x32_bf16 v[4:7], v[188:191], v[172:175], 0
	v_mfma_f32_16x16x32_bf16 v[56:59], v[184:187], v[152:155], v[56:59]
	v_mfma_f32_16x16x32_bf16 v[48:51], v[202:205], v[152:155], v[48:51]
	v_mfma_f32_16x16x32_bf16 v[40:43], v[184:187], v[160:163], v[40:43]
	v_mfma_f32_16x16x32_bf16 v[32:35], v[202:205], v[160:163], v[32:35]
	v_mfma_f32_16x16x32_bf16 v[24:27], v[184:187], v[168:171], v[24:27]
	v_mfma_f32_16x16x32_bf16 v[16:19], v[202:205], v[168:171], v[16:19]
	v_mfma_f32_16x16x32_bf16 v[8:11], v[184:187], v[176:179], v[8:11]
	v_mfma_f32_16x16x32_bf16 v[4:7], v[202:205], v[176:179], v[4:7]
	s_barrier
	s_add_i32 s52, 0, 0x18000
	v_add_u32_e32 v144, s52, v1
	ds_read_b128 v[132:135], v144
	ds_read_b128 v[136:139], v144 offset:1024
	ds_read_b128 v[140:143], v144 offset:2048
	ds_read_b128 v[144:147], v144 offset:3072
	s_add_u32 s24, s24, 0x80000
	s_addc_u32 s25, s25, 0
	ds_read_b128 v[148:151], v224 offset:32768
	ds_read_b128 v[152:155], v224 offset:33792
	ds_read_b128 v[156:159], v224 offset:34816
	ds_read_b128 v[160:163], v224 offset:35840
	ds_read_b128 v[164:167], v224 offset:36864
	ds_read_b128 v[168:171], v224 offset:37888
	ds_read_b128 v[172:175], v224 offset:38912
	ds_read_b128 v[176:179], v224 offset:39936
	s_mov_b32 m0, s36
	s_nop 0
	global_load_lds_dwordx4 v196, s[24:25]
	s_mov_b32 m0, s37
	s_nop 0
	global_load_lds_dwordx4 v194, s[24:25]
	s_add_i32 s24, 0, 0x1c000
	v_add_u32_e32 v202, s24, v1
	ds_read_b128 v[180:183], v202
	ds_read_b128 v[184:187], v202 offset:1024
	ds_read_b128 v[188:191], v202 offset:2048
	ds_read_b128 v[202:205], v202 offset:3072
	s_waitcnt lgkmcnt(0)
	s_barrier
	v_mfma_f32_16x16x32_bf16 v[128:131], v[132:135], v[148:151], v[128:131]
	v_mfma_f32_16x16x32_bf16 v[124:127], v[140:143], v[148:151], v[124:127]
	v_mfma_f32_16x16x32_bf16 v[112:115], v[132:135], v[156:159], v[112:115]
	v_mfma_f32_16x16x32_bf16 v[108:111], v[140:143], v[156:159], v[108:111]
	v_mfma_f32_16x16x32_bf16 v[100:103], v[132:135], v[164:167], v[100:103]
	v_mfma_f32_16x16x32_bf16 v[92:95], v[140:143], v[164:167], v[92:95]
	v_mfma_f32_16x16x32_bf16 v[84:87], v[132:135], v[172:175], v[84:87]
	v_mfma_f32_16x16x32_bf16 v[76:79], v[140:143], v[172:175], v[76:79]
	v_mfma_f32_16x16x32_bf16 v[128:131], v[136:139], v[152:155], v[128:131]
	v_mfma_f32_16x16x32_bf16 v[124:127], v[144:147], v[152:155], v[124:127]
	v_mfma_f32_16x16x32_bf16 v[112:115], v[136:139], v[160:163], v[112:115]
	v_mfma_f32_16x16x32_bf16 v[108:111], v[144:147], v[160:163], v[108:111]
	v_mfma_f32_16x16x32_bf16 v[100:103], v[136:139], v[168:171], v[100:103]
	v_mfma_f32_16x16x32_bf16 v[92:95], v[144:147], v[168:171], v[92:95]
	v_mfma_f32_16x16x32_bf16 v[84:87], v[136:139], v[176:179], v[84:87]
	v_mfma_f32_16x16x32_bf16 v[76:79], v[144:147], v[176:179], v[76:79]
	v_mfma_f32_16x16x32_bf16 v[120:123], v[180:183], v[148:151], v[120:123]
	v_mfma_f32_16x16x32_bf16 v[116:119], v[188:191], v[148:151], v[116:119]
	v_mfma_f32_16x16x32_bf16 v[104:107], v[180:183], v[156:159], v[104:107]
	v_mfma_f32_16x16x32_bf16 v[96:99], v[188:191], v[156:159], v[96:99]
	v_mfma_f32_16x16x32_bf16 v[88:91], v[180:183], v[164:167], v[88:91]
	v_mfma_f32_16x16x32_bf16 v[80:83], v[188:191], v[164:167], v[80:83]
	v_mfma_f32_16x16x32_bf16 v[72:75], v[180:183], v[172:175], v[72:75]
	v_mfma_f32_16x16x32_bf16 v[68:71], v[188:191], v[172:175], v[68:71]
	v_mfma_f32_16x16x32_bf16 v[120:123], v[184:187], v[152:155], v[120:123]
	v_mfma_f32_16x16x32_bf16 v[116:119], v[202:205], v[152:155], v[116:119]
	v_mfma_f32_16x16x32_bf16 v[104:107], v[184:187], v[160:163], v[104:107]
	v_mfma_f32_16x16x32_bf16 v[96:99], v[202:205], v[160:163], v[96:99]
	v_mfma_f32_16x16x32_bf16 v[88:91], v[184:187], v[168:171], v[88:91]
	v_mfma_f32_16x16x32_bf16 v[80:83], v[202:205], v[168:171], v[80:83]
	v_mfma_f32_16x16x32_bf16 v[72:75], v[184:187], v[176:179], v[72:75]
	v_mfma_f32_16x16x32_bf16 v[68:71], v[202:205], v[176:179], v[68:71]
	s_barrier
; #define PG8_STAGE(bufoff, gbase, voff) do { _Pragma("unroll") for (int _i = 0; _i < 2; ++_i) \
;         __builtin_amdgcn_global_load_lds((const unsigned*)((const char*)(gbase) + (voff)[_i]), (LAS unsigned*)(lds + (bufoff) + ldsw + _i * 8192), 16, 0, 0); } while (0)
; #define PG8_LDA(dst, b, h) do { _Pragma("unroll") for (int m = 0; m < 4; ++m) _Pragma("unroll") for (int k = 0; k < 2; ++k) dst[m][k] = *(const LAS bf16x8*)(lds + PG8_SA(b, h) + aoff + m * 2048 + k * 1024); } while (0)
; #define PG8_MMA(ai, bj, At, Bt) do { __builtin_amdgcn_s_setprio(1); _Pragma("unroll") for (int m = 0; m < 4; ++m) _Pragma("unroll") for (int n = 0; n < 2; ++n) _Pragma("unroll") for (int k = 0; k < 2; ++k) \
;         acc[ai][bj][m][n] = __builtin_amdgcn_mfma_f32_16x16x32_bf16(Bt[n][k], At[m][k], acc[ai][bj][m][n], 0, 0, 0); __builtin_amdgcn_s_setprio(0); } while (0)
; #define PG8_WAIT_V(n) asm volatile("s_waitcnt vmcnt(" #n ")" ::: "memory")
; #define PG8_WAIT_L(n) asm volatile("s_waitcnt lgkmcnt(" #n ")" ::: "memory")
; #define PG8_BAR __builtin_amdgcn_s_barrier()
; #define PG8_SCHED __builtin_amdgcn_sched_barrier(0)
; template <class Epi, class Sched>
; __device__ __forceinline__ void gemm_phase(LAS unsigned char* lds, const Gemm g, const Sched& S, const Epi& E) {
;     ...
;             PG8_LDA(At, 1, 1); PG8_STAGE(PG8_SA(1, 0), a3, voffA);
;             PG8_BAR; PG8_WAIT_L(0); PG8_MMA(1, 0, At, B0); PG8_BAR; PG8_SCHED;
;             PG8_STAGE(PG8_SB(1, 1), b3 + hstepB, voffB);
;             PG8_WAIT_V(6); PG8_BAR; PG8_MMA(1, 1, At, B1); PG8_BAR;
	ds_read_b128 v[148:151], v224 offset:49152
	ds_read_b128 v[152:155], v224 offset:50176
	ds_read_b128 v[156:159], v224 offset:51200
	ds_read_b128 v[160:163], v224 offset:52224
	ds_read_b128 v[164:167], v224 offset:53248
	ds_read_b128 v[168:171], v224 offset:54272
	ds_read_b128 v[172:175], v224 offset:55296
	ds_read_b128 v[176:179], v224 offset:56320
	s_add_i32 s25, s52, s30
	v_lshl_add_u64 v[206:207], v[206:207], 0, s[8:9]
	s_mov_b32 m0, s25
	s_nop 0
	global_load_lds_dwordx4 v[206:207], off
	v_lshl_add_u64 v[206:207], v[208:209], 0, s[8:9]
	s_add_i32 m0, s25, 0x2000
	s_nop 0
	global_load_lds_dwordx4 v[206:207], off
	s_mov_b32 m0, s42
	v_lshl_add_u64 v[206:207], v[210:211], 0, s[8:9]
	global_load_lds_dwordx4 v[206:207], off
	v_lshl_add_u64 v[206:207], v[212:213], 0, s[8:9]
	s_mov_b32 m0, s43
	s_nop 0
	global_load_lds_dwordx4 v[206:207], off
	s_add_u32 s20, s20, 0x80080
	s_addc_u32 s21, s21, 0
	s_add_i32 s24, s24, s30
	s_mov_b32 m0, s24
	s_nop 0
	global_load_lds_dwordx4 v2, s[20:21]
	s_add_i32 m0, s24, 0x2000
	s_nop 0
	global_load_lds_dwordx4 v192, s[20:21]
	s_add_i32 s51, s51, 2
	s_add_u32 s6, s6, 0x100
	s_addc_u32 s7, s7, 0
	s_add_u32 s49, s49, 0x100
	s_addc_u32 s50, s50, 0
	s_cmp_gt_u32 s51, 29
	s_waitcnt lgkmcnt(0)
	s_waitcnt vmcnt(6)
	s_barrier
	v_mfma_f32_16x16x32_bf16 v[64:67], v[132:135], v[148:151], v[64:67]
	v_mfma_f32_16x16x32_bf16 v[60:63], v[140:143], v[148:151], v[60:63]
	v_mfma_f32_16x16x32_bf16 v[52:55], v[132:135], v[156:159], v[52:55]
	v_mfma_f32_16x16x32_bf16 v[44:47], v[140:143], v[156:159], v[44:47]
	v_mfma_f32_16x16x32_bf16 v[36:39], v[132:135], v[164:167], v[36:39]
	v_mfma_f32_16x16x32_bf16 v[28:31], v[140:143], v[164:167], v[28:31]
	v_mfma_f32_16x16x32_bf16 v[20:23], v[132:135], v[172:175], v[20:23]
	v_mfma_f32_16x16x32_bf16 v[12:15], v[140:143], v[172:175], v[12:15]
	v_mfma_f32_16x16x32_bf16 v[64:67], v[136:139], v[152:155], v[64:67]
	v_mfma_f32_16x16x32_bf16 v[60:63], v[144:147], v[152:155], v[60:63]
	v_mfma_f32_16x16x32_bf16 v[52:55], v[136:139], v[160:163], v[52:55]
	v_mfma_f32_16x16x32_bf16 v[44:47], v[144:147], v[160:163], v[44:47]
	v_mfma_f32_16x16x32_bf16 v[36:39], v[136:139], v[168:171], v[36:39]
	v_mfma_f32_16x16x32_bf16 v[28:31], v[144:147], v[168:171], v[28:31]
	v_mfma_f32_16x16x32_bf16 v[20:23], v[136:139], v[176:179], v[20:23]
	v_mfma_f32_16x16x32_bf16 v[12:15], v[144:147], v[176:179], v[12:15]
	v_mfma_f32_16x16x32_bf16 v[56:59], v[180:183], v[148:151], v[56:59]
	v_mfma_f32_16x16x32_bf16 v[48:51], v[188:191], v[148:151], v[48:51]
	v_mfma_f32_16x16x32_bf16 v[40:43], v[180:183], v[156:159], v[40:43]
	v_mfma_f32_16x16x32_bf16 v[32:35], v[188:191], v[156:159], v[32:35]
	v_mfma_f32_16x16x32_bf16 v[24:27], v[180:183], v[164:167], v[24:27]
	v_mfma_f32_16x16x32_bf16 v[16:19], v[188:191], v[164:167], v[16:19]
	v_mfma_f32_16x16x32_bf16 v[8:11], v[180:183], v[172:175], v[8:11]
	v_mfma_f32_16x16x32_bf16 v[4:7], v[188:191], v[172:175], v[4:7]
	v_mfma_f32_16x16x32_bf16 v[56:59], v[184:187], v[152:155], v[56:59]
	v_mfma_f32_16x16x32_bf16 v[48:51], v[202:205], v[152:155], v[48:51]
	v_mfma_f32_16x16x32_bf16 v[40:43], v[184:187], v[160:163], v[40:43]
	v_mfma_f32_16x16x32_bf16 v[32:35], v[202:205], v[160:163], v[32:35]
	v_mfma_f32_16x16x32_bf16 v[24:27], v[184:187], v[168:171], v[24:27]
	v_mfma_f32_16x16x32_bf16 v[16:19], v[202:205], v[168:171], v[16:19]
	v_mfma_f32_16x16x32_bf16 v[8:11], v[184:187], v[176:179], v[8:11]
	v_mfma_f32_16x16x32_bf16 v[4:7], v[202:205], v[176:179], v[4:7]
	s_barrier
	s_setprio 0

;     __device__ __forceinline__ void prefetch(const Unit& u, int ui) const { if (rs) rs_prefetch(rs, u.pm, ui); }
;     __device__ __forceinline__ void prefetch(const Unit& u, int ui) const { rs_prefetch(rs, u.pm, ui); }
; #define PG8_STAGE(bufoff, gbase, voff) do { _Pragma("unroll") for (int _i = 0; _i < 2; ++_i) \
;         __builtin_amdgcn_global_load_lds((const unsigned*)((const char*)(gbase) + (voff)[_i]), (LAS unsigned*)(lds + (bufoff) + ldsw + _i * 8192), 16, 0, 0); } while (0)
; #define PG8_LDA(dst, b, h) do { _Pragma("unroll") for (int m = 0; m < 4; ++m) _Pragma("unroll") for (int k = 0; k < 2; ++k) dst[m][k] = *(const LAS bf16x8*)(lds + PG8_SA(b, h) + aoff + m * 2048 + k * 1024); } while (0)
; #define PG8_LDB(dst, b, h) do { _Pragma("unroll") for (int n = 0; n < 2; ++n) _Pragma("unroll") for (int k = 0; k < 2; ++k) dst[n][k] = *(const LAS bf16x8*)(lds + PG8_SB(b, h) + boff + n * 2048 + k * 1024); } while (0)
; template <class Epi, class Sched>
; __device__ __forceinline__ void gemm_phase(LAS unsigned char* lds, const Gemm g, const Sched& S, const Epi& E) {
;     ...
;     for (;;) {
;         E.prefetch(cur, ui);
;         const bool has_next = S.next(ui + 1, nxt);
;         const char* nA = has_next ? (const char*)g.A + (size_t)nxt.pm * tstepA : cA; const char* nB = has_next ? (const char*)g.Bt + (size_t)nxt.pn * tstepB : cB;
;         for (int t = 0; t < nt; t += 2) {
;             const bool last = (t == nt - 2);
;             const char* a1 = cA + (size_t)(t + 1) * kstep;
;             const char* a2 = last ? nA : cA + (size_t)(t + 2) * kstep; const char* b2 = last ? nB : cB + (size_t)(t + 2) * kstep;
;             const char* a3 = a2 + kstep; const char* b3 = b2 + kstep;
;             if (last && has_next) S.a_ready(nxt);
;             PG8_LDB(B0, 0, 0); PG8_SCHED; PG8_LDA(At, 0, 0); PG8_STAGE(PG8_SA(1, 1), a1 + hstepA, voffA);
;             PG8_WAIT_L(8); PG8_BAR; PG8_WAIT_L(0); PG8_MMA(0, 0, At, B0); PG8_BAR; PG8_SCHED;
;             PG8_LDB(B1, 0, 1); PG8_STAGE(PG8_SB(0, 0), b2, voffB);
;             PG8_BAR; PG8_WAIT_L(0); PG8_MMA(0, 1, At, B1); PG8_BAR;
;             PG8_LDA(At, 0, 1); PG8_STAGE(PG8_SA(0, 0), a2, voffA);
;             PG8_BAR; PG8_WAIT_L(0); PG8_MMA(1, 0, At, B0); PG8_BAR; PG8_SCHED;
;             PG8_STAGE(PG8_SB(0, 1), b2 + hstepB, voffB);
;             PG8_WAIT_V(6); PG8_BAR; PG8_MMA(1, 1, At, B1); PG8_BAR;
.LBB0_1525:
	v_mov_b64_e32 v[4:5], 0x1600
	s_ashr_i32 s57, s56, 31
	v_cmp_lt_i64_e32 vcc, s[14:15], v[4:5]
	s_lshl_b64 s[14:15], s[56:57], 20
	s_add_u32 s58, s88, s14
	s_addc_u32 s59, s89, s15
	s_and_b64 s[14:15], vcc, exec
	s_cselect_b32 s57, s59, s5
	s_cselect_b32 s67, s58, s4
	s_ashr_i32 s55, s54, 31
	s_lshl_b64 s[14:15], s[54:55], 20
	s_add_u32 s60, s2, s14
	s_addc_u32 s61, s18, s15
	s_and_b64 s[14:15], vcc, exec
	s_cselect_b32 s55, s61, s7
	s_cselect_b32 s68, s60, s6
	s_add_u32 s4, s4, 0x80080
	s_addc_u32 s5, s5, 0
	s_add_u32 s69, s6, 0x100
	s_addc_u32 s70, s7, 0
	s_mov_b32 s71, -2
	s_add_u32 s6, s4, 0xfff80080
	s_addc_u32 s7, s5, -1
	s_add_i32 s72, 0, 0x10000
	v_add_u32_e32 v2, s72, v1
	ds_read_b128 v[132:135], v2
	ds_read_b128 v[136:139], v2 offset:1024
	ds_read_b128 v[140:143], v2 offset:2048
	ds_read_b128 v[144:147], v2 offset:3072
	s_cmp_eq_u32 s71, 28
	s_cselect_b32 s15, s57, s7
	s_cselect_b32 s14, s67, s6
	s_cselect_b32 s7, s55, s70
	s_cselect_b32 s6, s68, s69
	ds_read_b128 v[148:151], v207
	ds_read_b128 v[152:155], v207 offset:1024
	ds_read_b128 v[156:159], v207 offset:2048
	ds_read_b128 v[160:163], v207 offset:3072
	ds_read_b128 v[164:167], v207 offset:4096
	ds_read_b128 v[168:171], v207 offset:5120
	ds_read_b128 v[186:189], v207 offset:6144
	ds_read_b128 v[190:193], v207 offset:7168
	s_add_i32 s74, 0, 0x14000
	v_add_u32_e32 v2, s74, v1
	ds_read_b128 v[194:197], v2
	ds_read_b128 v[198:201], v2 offset:1024
	ds_read_b128 v[202:205], v2 offset:2048
	ds_read_b128 v[208:211], v2 offset:3072
	s_add_i32 m0, s20, 0xc000
	s_nop 0
	global_load_lds_dwordx4 v182, s[4:5]
	s_add_i32 m0, s20, 0xe000
	s_nop 0
	global_load_lds_dwordx4 v184, s[4:5]
	s_nop 0
	s_waitcnt lgkmcnt(0)
	s_barrier
	v_mfma_f32_16x16x32_bf16 v[68:71], v[132:135], v[148:151], 0
	v_mfma_f32_16x16x32_bf16 v[72:75], v[140:143], v[148:151], 0
	v_mfma_f32_16x16x32_bf16 v[120:123], v[132:135], v[156:159], 0
	v_mfma_f32_16x16x32_bf16 v[116:119], v[140:143], v[156:159], 0
	v_mfma_f32_16x16x32_bf16 v[112:115], v[132:135], v[164:167], 0
	v_mfma_f32_16x16x32_bf16 v[108:111], v[140:143], v[164:167], 0
	v_mfma_f32_16x16x32_bf16 v[104:107], v[132:135], v[186:189], 0
	v_mfma_f32_16x16x32_bf16 v[100:103], v[140:143], v[186:189], 0
	v_mfma_f32_16x16x32_bf16 v[68:71], v[136:139], v[152:155], v[68:71]
	v_mfma_f32_16x16x32_bf16 v[72:75], v[144:147], v[152:155], v[72:75]
	v_mfma_f32_16x16x32_bf16 v[120:123], v[136:139], v[160:163], v[120:123]
	v_mfma_f32_16x16x32_bf16 v[116:119], v[144:147], v[160:163], v[116:119]
	v_mfma_f32_16x16x32_bf16 v[112:115], v[136:139], v[168:171], v[112:115]
	v_mfma_f32_16x16x32_bf16 v[108:111], v[144:147], v[168:171], v[108:111]
	v_mfma_f32_16x16x32_bf16 v[104:107], v[136:139], v[190:193], v[104:107]
	v_mfma_f32_16x16x32_bf16 v[100:103], v[144:147], v[190:193], v[100:103]
	v_mfma_f32_16x16x32_bf16 v[76:79], v[194:197], v[148:151], 0
	v_mfma_f32_16x16x32_bf16 v[80:83], v[202:205], v[148:151], 0
	v_mfma_f32_16x16x32_bf16 v[96:99], v[194:197], v[156:159], 0
	v_mfma_f32_16x16x32_bf16 v[92:95], v[202:205], v[156:159], 0
	v_mfma_f32_16x16x32_bf16 v[88:91], v[194:197], v[164:167], 0
	v_mfma_f32_16x16x32_bf16 v[84:87], v[202:205], v[164:167], 0
	v_mfma_f32_16x16x32_bf16 v[128:131], v[194:197], v[186:189], 0
	v_mfma_f32_16x16x32_bf16 v[124:127], v[202:205], v[186:189], 0
	v_mfma_f32_16x16x32_bf16 v[76:79], v[198:201], v[152:155], v[76:79]
	v_mfma_f32_16x16x32_bf16 v[80:83], v[208:211], v[152:155], v[80:83]
	v_mfma_f32_16x16x32_bf16 v[96:99], v[198:201], v[160:163], v[96:99]
	v_mfma_f32_16x16x32_bf16 v[92:95], v[208:211], v[160:163], v[92:95]
	v_mfma_f32_16x16x32_bf16 v[88:91], v[198:201], v[168:171], v[88:91]
	v_mfma_f32_16x16x32_bf16 v[84:87], v[208:211], v[168:171], v[84:87]
	v_mfma_f32_16x16x32_bf16 v[128:131], v[198:201], v[190:193], v[128:131]
	v_mfma_f32_16x16x32_bf16 v[124:127], v[208:211], v[190:193], v[124:127]
	s_barrier
	ds_read_b128 v[148:151], v207 offset:16384
	ds_read_b128 v[152:155], v207 offset:17408
	ds_read_b128 v[156:159], v207 offset:18432
	ds_read_b128 v[160:163], v207 offset:19456
	ds_read_b128 v[164:167], v207 offset:20480
	ds_read_b128 v[168:171], v207 offset:21504
	ds_read_b128 v[186:189], v207 offset:22528
	ds_read_b128 v[190:193], v207 offset:23552
	s_add_i32 s72, s72, s19
	v_lshl_add_u64 v[172:173], s[6:7], 0, v[178:179]
	s_mov_b32 m0, s72
	s_nop 0
	global_load_lds_dwordx4 v[172:173], off
	v_lshl_add_u64 v[212:213], s[6:7], 0, v[174:175]
	s_add_i32 m0, s72, 0x2000
	s_nop 0
	global_load_lds_dwordx4 v[212:213], off
	s_mov_b32 m0, s20
	v_lshl_add_u64 v[216:217], s[14:15], 0, v[180:181]
	global_load_lds_dwordx4 v[216:217], off
	v_lshl_add_u64 v[218:219], s[14:15], 0, v[176:177]
	s_mov_b32 m0, s21
	s_nop 0
	global_load_lds_dwordx4 v[218:219], off
	s_add_u32 s72, s6, 0x80000
	s_addc_u32 s73, s7, 0
	s_add_i32 s74, s74, s19
	s_mov_b32 m0, s74
	s_nop 0
	global_load_lds_dwordx4 v178, s[72:73]
	s_add_i32 m0, s74, 0x2000
	s_nop 0
	global_load_lds_dwordx4 v174, s[72:73]
	s_waitcnt lgkmcnt(0)
	s_waitcnt vmcnt(6)
	s_barrier
; #define PG8_STAGE(bufoff, gbase, voff) do { _Pragma("unroll") for (int _i = 0; _i < 2; ++_i) \
;         __builtin_amdgcn_global_load_lds((const unsigned*)((const char*)(gbase) + (voff)[_i]), (LAS unsigned*)(lds + (bufoff) + ldsw + _i * 8192), 16, 0, 0); } while (0)
; #define PG8_LDA(dst, b, h) do { _Pragma("unroll") for (int m = 0; m < 4; ++m) _Pragma("unroll") for (int k = 0; k < 2; ++k) dst[m][k] = *(const LAS bf16x8*)(lds + PG8_SA(b, h) + aoff + m * 2048 + k * 1024); } while (0)
; #define PG8_LDB(dst, b, h) do { _Pragma("unroll") for (int n = 0; n < 2; ++n) _Pragma("unroll") for (int k = 0; k < 2; ++k) dst[n][k] = *(const LAS bf16x8*)(lds + PG8_SB(b, h) + boff + n * 2048 + k * 1024); } while (0)
; #define PG8_MMA(ai, bj, At, Bt) do { __builtin_amdgcn_s_setprio(1); _Pragma("unroll") for (int m = 0; m < 4; ++m) _Pragma("unroll") for (int n = 0; n < 2; ++n) _Pragma("unroll") for (int k = 0; k < 2; ++k) \
;         acc[ai][bj][m][n] = __builtin_amdgcn_mfma_f32_16x16x32_bf16(Bt[n][k], At[m][k], acc[ai][bj][m][n], 0, 0, 0); __builtin_amdgcn_s_setprio(0); } while (0)
; #define PG8_WAIT_V(n) asm volatile("s_waitcnt vmcnt(" #n ")" ::: "memory")
; #define PG8_WAIT_L(n) asm volatile("s_waitcnt lgkmcnt(" #n ")" ::: "memory")
; #define PG8_BAR __builtin_amdgcn_s_barrier()
; #define PG8_SCHED __builtin_amdgcn_sched_barrier(0)
; template <class Epi, class Sched>
; __device__ __forceinline__ void gemm_phase(LAS unsigned char* lds, const Gemm g, const Sched& S, const Epi& E) {
;     ...
;             PG8_BAR; PG8_WAIT_L(0); PG8_MMA(1, 0, At, B0); PG8_BAR; PG8_SCHED;
;             PG8_STAGE(PG8_SB(0, 1), b2 + hstepB, voffB);
;             PG8_WAIT_V(6); PG8_BAR; PG8_MMA(1, 1, At, B1); PG8_BAR;
;             PG8_LDB(B0, 1, 0); PG8_SCHED; PG8_LDA(At, 1, 0); PG8_STAGE(PG8_SA(0, 1), a2 + hstepA, voffA);
;             PG8_WAIT_L(8); PG8_BAR; PG8_WAIT_L(0); PG8_MMA(0, 0, At, B0); PG8_BAR; PG8_SCHED;
;             PG8_LDB(B1, 1, 1); PG8_STAGE(PG8_SB(1, 0), b3, voffB);
;             PG8_BAR; PG8_WAIT_L(0); PG8_MMA(0, 1, At, B1); PG8_BAR;
	v_mfma_f32_16x16x32_bf16 v[56:59], v[132:135], v[148:151], 0
	v_mfma_f32_16x16x32_bf16 v[52:55], v[140:143], v[148:151], 0
	v_mfma_f32_16x16x32_bf16 v[48:51], v[132:135], v[156:159], 0
	v_mfma_f32_16x16x32_bf16 v[44:47], v[140:143], v[156:159], 0
	v_mfma_f32_16x16x32_bf16 v[40:43], v[132:135], v[164:167], 0
	v_mfma_f32_16x16x32_bf16 v[36:39], v[140:143], v[164:167], 0
	v_mfma_f32_16x16x32_bf16 v[32:35], v[132:135], v[186:189], 0
	v_mfma_f32_16x16x32_bf16 v[28:31], v[140:143], v[186:189], 0
	v_mfma_f32_16x16x32_bf16 v[56:59], v[136:139], v[152:155], v[56:59]
	v_mfma_f32_16x16x32_bf16 v[52:55], v[144:147], v[152:155], v[52:55]
	v_mfma_f32_16x16x32_bf16 v[48:51], v[136:139], v[160:163], v[48:51]
	v_mfma_f32_16x16x32_bf16 v[44:47], v[144:147], v[160:163], v[44:47]
	v_mfma_f32_16x16x32_bf16 v[40:43], v[136:139], v[168:171], v[40:43]
	v_mfma_f32_16x16x32_bf16 v[36:39], v[144:147], v[168:171], v[36:39]
	v_mfma_f32_16x16x32_bf16 v[32:35], v[136:139], v[190:193], v[32:35]
	v_mfma_f32_16x16x32_bf16 v[28:31], v[144:147], v[190:193], v[28:31]
	v_mfma_f32_16x16x32_bf16 v[24:27], v[194:197], v[148:151], 0
	v_mfma_f32_16x16x32_bf16 v[20:23], v[202:205], v[148:151], 0
	v_mfma_f32_16x16x32_bf16 v[16:19], v[194:197], v[156:159], 0
	v_mfma_f32_16x16x32_bf16 v[12:15], v[202:205], v[156:159], 0
	v_mfma_f32_16x16x32_bf16 v[8:11], v[194:197], v[164:167], 0
	v_mfma_f32_16x16x32_bf16 v[4:7], v[202:205], v[164:167], 0
	v_mfma_f32_16x16x32_bf16 v[60:63], v[194:197], v[186:189], 0
	v_mfma_f32_16x16x32_bf16 v[64:67], v[202:205], v[186:189], 0
	v_mfma_f32_16x16x32_bf16 v[24:27], v[198:201], v[152:155], v[24:27]
	v_mfma_f32_16x16x32_bf16 v[20:23], v[208:211], v[152:155], v[20:23]
	v_mfma_f32_16x16x32_bf16 v[16:19], v[198:201], v[160:163], v[16:19]
	v_mfma_f32_16x16x32_bf16 v[12:15], v[208:211], v[160:163], v[12:15]
	v_mfma_f32_16x16x32_bf16 v[8:11], v[198:201], v[168:171], v[8:11]
	v_mfma_f32_16x16x32_bf16 v[4:7], v[208:211], v[168:171], v[4:7]
	v_mfma_f32_16x16x32_bf16 v[60:63], v[198:201], v[190:193], v[60:63]
	v_mfma_f32_16x16x32_bf16 v[64:67], v[208:211], v[190:193], v[64:67]
	s_barrier
	s_add_i32 s72, 0, 0x18000
	v_add_u32_e32 v2, s72, v1
	ds_read_b128 v[132:135], v2
	ds_read_b128 v[136:139], v2 offset:1024
	ds_read_b128 v[140:143], v2 offset:2048
	ds_read_b128 v[144:147], v2 offset:3072
	s_add_u32 s14, s14, 0x80000
	s_addc_u32 s15, s15, 0
	ds_read_b128 v[148:151], v207 offset:32768
	ds_read_b128 v[152:155], v207 offset:33792
	ds_read_b128 v[156:159], v207 offset:34816
	ds_read_b128 v[160:163], v207 offset:35840
	ds_read_b128 v[164:167], v207 offset:36864
	ds_read_b128 v[168:171], v207 offset:37888
	ds_read_b128 v[186:189], v207 offset:38912
	ds_read_b128 v[190:193], v207 offset:39936
	s_mov_b32 m0, s24
	s_nop 0
	global_load_lds_dwordx4 v180, s[14:15]
	s_mov_b32 m0, s25
	s_nop 0
	global_load_lds_dwordx4 v176, s[14:15]
	s_add_i32 s14, 0, 0x1c000
	v_add_u32_e32 v2, s14, v1
	ds_read_b128 v[194:197], v2
	ds_read_b128 v[198:201], v2 offset:1024
	ds_read_b128 v[202:205], v2 offset:2048
	ds_read_b128 v[208:211], v2 offset:3072
	s_waitcnt lgkmcnt(0)
	s_barrier
	v_mfma_f32_16x16x32_bf16 v[68:71], v[132:135], v[148:151], v[68:71]
	v_mfma_f32_16x16x32_bf16 v[72:75], v[140:143], v[148:151], v[72:75]
	v_mfma_f32_16x16x32_bf16 v[120:123], v[132:135], v[156:159], v[120:123]
	v_mfma_f32_16x16x32_bf16 v[116:119], v[140:143], v[156:159], v[116:119]
	v_mfma_f32_16x16x32_bf16 v[112:115], v[132:135], v[164:167], v[112:115]
	v_mfma_f32_16x16x32_bf16 v[108:111], v[140:143], v[164:167], v[108:111]
	v_mfma_f32_16x16x32_bf16 v[104:107], v[132:135], v[186:189], v[104:107]
	v_mfma_f32_16x16x32_bf16 v[100:103], v[140:143], v[186:189], v[100:103]
	v_mfma_f32_16x16x32_bf16 v[68:71], v[136:139], v[152:155], v[68:71]
	v_mfma_f32_16x16x32_bf16 v[72:75], v[144:147], v[152:155], v[72:75]
	v_mfma_f32_16x16x32_bf16 v[120:123], v[136:139], v[160:163], v[120:123]
	v_mfma_f32_16x16x32_bf16 v[116:119], v[144:147], v[160:163], v[116:119]
	v_mfma_f32_16x16x32_bf16 v[112:115], v[136:139], v[168:171], v[112:115]
	v_mfma_f32_16x16x32_bf16 v[108:111], v[144:147], v[168:171], v[108:111]
	v_mfma_f32_16x16x32_bf16 v[104:107], v[136:139], v[190:193], v[104:107]
	v_mfma_f32_16x16x32_bf16 v[100:103], v[144:147], v[190:193], v[100:103]
	v_mfma_f32_16x16x32_bf16 v[76:79], v[194:197], v[148:151], v[76:79]
	v_mfma_f32_16x16x32_bf16 v[80:83], v[202:205], v[148:151], v[80:83]
	v_mfma_f32_16x16x32_bf16 v[96:99], v[194:197], v[156:159], v[96:99]
	v_mfma_f32_16x16x32_bf16 v[92:95], v[202:205], v[156:159], v[92:95]
	v_mfma_f32_16x16x32_bf16 v[88:91], v[194:197], v[164:167], v[88:91]
	v_mfma_f32_16x16x32_bf16 v[84:87], v[202:205], v[164:167], v[84:87]
	v_mfma_f32_16x16x32_bf16 v[128:131], v[194:197], v[186:189], v[128:131]
	v_mfma_f32_16x16x32_bf16 v[124:127], v[202:205], v[186:189], v[124:127]
	v_mfma_f32_16x16x32_bf16 v[76:79], v[198:201], v[152:155], v[76:79]
	v_mfma_f32_16x16x32_bf16 v[80:83], v[208:211], v[152:155], v[80:83]
	v_mfma_f32_16x16x32_bf16 v[96:99], v[198:201], v[160:163], v[96:99]
	v_mfma_f32_16x16x32_bf16 v[92:95], v[208:211], v[160:163], v[92:95]
	v_mfma_f32_16x16x32_bf16 v[88:91], v[198:201], v[168:171], v[88:91]
	v_mfma_f32_16x16x32_bf16 v[84:87], v[208:211], v[168:171], v[84:87]
	v_mfma_f32_16x16x32_bf16 v[128:131], v[198:201], v[190:193], v[128:131]
	v_mfma_f32_16x16x32_bf16 v[124:127], v[208:211], v[190:193], v[124:127]
	s_barrier
; #define PG8_STAGE(bufoff, gbase, voff) do { _Pragma("unroll") for (int _i = 0; _i < 2; ++_i) \
;         __builtin_amdgcn_global_load_lds((const unsigned*)((const char*)(gbase) + (voff)[_i]), (LAS unsigned*)(lds + (bufoff) + ldsw + _i * 8192), 16, 0, 0); } while (0)
; #define PG8_LDA(dst, b, h) do { _Pragma("unroll") for (int m = 0; m < 4; ++m) _Pragma("unroll") for (int k = 0; k < 2; ++k) dst[m][k] = *(const LAS bf16x8*)(lds + PG8_SA(b, h) + aoff + m * 2048 + k * 1024); } while (0)
; #define PG8_MMA(ai, bj, At, Bt) do { __builtin_amdgcn_s_setprio(1); _Pragma("unroll") for (int m = 0; m < 4; ++m) _Pragma("unroll") for (int n = 0; n < 2; ++n) _Pragma("unroll") for (int k = 0; k < 2; ++k) \
;         acc[ai][bj][m][n] = __builtin_amdgcn_mfma_f32_16x16x32_bf16(Bt[n][k], At[m][k], acc[ai][bj][m][n], 0, 0, 0); __builtin_amdgcn_s_setprio(0); } while (0)
; #define PG8_WAIT_V(n) asm volatile("s_waitcnt vmcnt(" #n ")" ::: "memory")
; #define PG8_WAIT_L(n) asm volatile("s_waitcnt lgkmcnt(" #n ")" ::: "memory")
; #define PG8_BAR __builtin_amdgcn_s_barrier()
; #define PG8_SCHED __builtin_amdgcn_sched_barrier(0)
; template <class Epi, class Sched>
; __device__ __forceinline__ void gemm_phase(LAS unsigned char* lds, const Gemm g, const Sched& S, const Epi& E) {
;     ...
;             PG8_LDA(At, 1, 1); PG8_STAGE(PG8_SA(1, 0), a3, voffA);
;             PG8_BAR; PG8_WAIT_L(0); PG8_MMA(1, 0, At, B0); PG8_BAR; PG8_SCHED;
;             PG8_STAGE(PG8_SB(1, 1), b3 + hstepB, voffB);
;             PG8_WAIT_V(6); PG8_BAR; PG8_MMA(1, 1, At, B1); PG8_BAR;
	ds_read_b128 v[148:151], v207 offset:49152
	ds_read_b128 v[152:155], v207 offset:50176
	ds_read_b128 v[156:159], v207 offset:51200
	ds_read_b128 v[160:163], v207 offset:52224
	ds_read_b128 v[164:167], v207 offset:53248
	ds_read_b128 v[168:171], v207 offset:54272
	ds_read_b128 v[186:189], v207 offset:55296
	ds_read_b128 v[190:193], v207 offset:56320
	s_add_i32 s15, s72, s19
	v_lshl_add_u64 v[172:173], v[172:173], 0, s[8:9]
	s_mov_b32 m0, s15
	s_nop 0
	global_load_lds_dwordx4 v[172:173], off
	v_lshl_add_u64 v[172:173], v[212:213], 0, s[8:9]
	s_add_i32 m0, s15, 0x2000
	s_nop 0
	global_load_lds_dwordx4 v[172:173], off
	s_mov_b32 m0, s30
	v_lshl_add_u64 v[172:173], v[216:217], 0, s[8:9]
	global_load_lds_dwordx4 v[172:173], off
	v_lshl_add_u64 v[172:173], v[218:219], 0, s[8:9]
	s_mov_b32 m0, s31
	s_nop 0
	global_load_lds_dwordx4 v[172:173], off
	s_add_u32 s6, s6, 0x80080
	s_addc_u32 s7, s7, 0
	s_add_i32 s14, s14, s19
	s_mov_b32 m0, s14
	s_nop 0
	global_load_lds_dwordx4 v178, s[6:7]
	s_add_i32 m0, s14, 0x2000
	s_nop 0
	global_load_lds_dwordx4 v174, s[6:7]
	s_add_i32 s71, s71, 2
	s_add_u32 s4, s4, 0x100
	s_addc_u32 s5, s5, 0
	s_add_u32 s69, s69, 0x100
	s_addc_u32 s70, s70, 0
	s_cmp_gt_u32 s71, 29
	s_waitcnt lgkmcnt(0)
	s_waitcnt vmcnt(6)
	s_barrier
	v_mfma_f32_16x16x32_bf16 v[56:59], v[132:135], v[148:151], v[56:59]
	v_mfma_f32_16x16x32_bf16 v[52:55], v[140:143], v[148:151], v[52:55]
	v_mfma_f32_16x16x32_bf16 v[48:51], v[132:135], v[156:159], v[48:51]
	v_mfma_f32_16x16x32_bf16 v[44:47], v[140:143], v[156:159], v[44:47]
	v_mfma_f32_16x16x32_bf16 v[40:43], v[132:135], v[164:167], v[40:43]
	v_mfma_f32_16x16x32_bf16 v[36:39], v[140:143], v[164:167], v[36:39]
	v_mfma_f32_16x16x32_bf16 v[32:35], v[132:135], v[186:189], v[32:35]
	v_mfma_f32_16x16x32_bf16 v[28:31], v[140:143], v[186:189], v[28:31]
	v_mfma_f32_16x16x32_bf16 v[56:59], v[136:139], v[152:155], v[56:59]
	v_mfma_f32_16x16x32_bf16 v[52:55], v[144:147], v[152:155], v[52:55]
	v_mfma_f32_16x16x32_bf16 v[48:51], v[136:139], v[160:163], v[48:51]
	v_mfma_f32_16x16x32_bf16 v[44:47], v[144:147], v[160:163], v[44:47]
	v_mfma_f32_16x16x32_bf16 v[40:43], v[136:139], v[168:171], v[40:43]
	v_mfma_f32_16x16x32_bf16 v[36:39], v[144:147], v[168:171], v[36:39]
	v_mfma_f32_16x16x32_bf16 v[32:35], v[136:139], v[190:193], v[32:35]
	v_mfma_f32_16x16x32_bf16 v[28:31], v[144:147], v[190:193], v[28:31]
	v_mfma_f32_16x16x32_bf16 v[24:27], v[194:197], v[148:151], v[24:27]
	v_mfma_f32_16x16x32_bf16 v[20:23], v[202:205], v[148:151], v[20:23]
	v_mfma_f32_16x16x32_bf16 v[16:19], v[194:197], v[156:159], v[16:19]
	v_mfma_f32_16x16x32_bf16 v[12:15], v[202:205], v[156:159], v[12:15]
	v_mfma_f32_16x16x32_bf16 v[8:11], v[194:197], v[164:167], v[8:11]
	v_mfma_f32_16x16x32_bf16 v[4:7], v[202:205], v[164:167], v[4:7]
	v_mfma_f32_16x16x32_bf16 v[60:63], v[194:197], v[186:189], v[60:63]
	v_mfma_f32_16x16x32_bf16 v[64:67], v[202:205], v[186:189], v[64:67]
	v_mfma_f32_16x16x32_bf16 v[24:27], v[198:201], v[152:155], v[24:27]
	v_mfma_f32_16x16x32_bf16 v[20:23], v[208:211], v[152:155], v[20:23]
	v_mfma_f32_16x16x32_bf16 v[16:19], v[198:201], v[160:163], v[16:19]
	v_mfma_f32_16x16x32_bf16 v[12:15], v[208:211], v[160:163], v[12:15]
	v_mfma_f32_16x16x32_bf16 v[8:11], v[198:201], v[168:171], v[8:11]
	v_mfma_f32_16x16x32_bf16 v[4:7], v[208:211], v[168:171], v[4:7]
	v_mfma_f32_16x16x32_bf16 v[60:63], v[198:201], v[190:193], v[60:63]
	v_mfma_f32_16x16x32_bf16 v[64:67], v[208:211], v[190:193], v[64:67]
	s_barrier
	s_setprio 0
